# plus EpiScale epilogues of P1, MLP-up x2, kv_up: all 8 rows' sum-of-squares partial loads and the row-scale shuffle reductions hoisted to the epilogue top (one round trip instead of 16)
# baseline (speedup 1.0000x reference)
.LBB0_852:
	v_lshl_add_u32 v148, s70, 8, v150
	v_ashrrev_i32_e32 v149, 31, v148
	v_mov_b32_e32 v227, 0
	v_mov_b32_e32 v226, v148
	v_lshlrev_b64 v[228:229], 7, v[226:227]
	v_lshl_add_u64 v[228:229], s[52:53], 0, v[228:229]
	v_lshl_add_u64 v[228:229], v[136:137], 4, v[228:229]
	global_load_dwordx4 v[166:169], v[228:229], off
	global_load_dwordx4 v[170:173], v[228:229], off offset:64
	v_add_u32_e32 v226, 16, v148
	v_lshlrev_b64 v[228:229], 7, v[226:227]
	v_lshl_add_u64 v[228:229], s[52:53], 0, v[228:229]
	v_lshl_add_u64 v[228:229], v[136:137], 4, v[228:229]
	global_load_dwordx4 v[174:177], v[228:229], off
	global_load_dwordx4 v[178:181], v[228:229], off offset:64
	v_add_u32_e32 v226, 32, v148
	v_lshlrev_b64 v[228:229], 7, v[226:227]
	v_lshl_add_u64 v[228:229], s[52:53], 0, v[228:229]
	v_lshl_add_u64 v[228:229], v[136:137], 4, v[228:229]
	global_load_dwordx4 v[182:185], v[228:229], off
	global_load_dwordx4 v[186:189], v[228:229], off offset:64
	v_add_u32_e32 v226, 48, v148
	v_lshlrev_b64 v[228:229], 7, v[226:227]
	v_lshl_add_u64 v[228:229], s[52:53], 0, v[228:229]
	v_lshl_add_u64 v[228:229], v[136:137], 4, v[228:229]
	global_load_dwordx4 v[190:193], v[228:229], off
	global_load_dwordx4 v[194:197], v[228:229], off offset:64
	v_add_u32_e32 v226, 128, v148
	v_lshlrev_b64 v[228:229], 7, v[226:227]
	v_lshl_add_u64 v[228:229], s[52:53], 0, v[228:229]
	v_lshl_add_u64 v[228:229], v[136:137], 4, v[228:229]
	global_load_dwordx4 v[198:201], v[228:229], off
	global_load_dwordx4 v[202:205], v[228:229], off offset:64
	v_add_u32_e32 v226, 144, v148
	v_lshlrev_b64 v[228:229], 7, v[226:227]
	v_lshl_add_u64 v[228:229], s[52:53], 0, v[228:229]
	v_lshl_add_u64 v[228:229], v[136:137], 4, v[228:229]
	global_load_dwordx4 v[206:209], v[228:229], off
	global_load_dwordx4 v[210:213], v[228:229], off offset:64
	v_add_u32_e32 v226, 160, v148
	v_lshlrev_b64 v[228:229], 7, v[226:227]
	v_lshl_add_u64 v[228:229], s[52:53], 0, v[228:229]
	v_lshl_add_u64 v[228:229], v[136:137], 4, v[228:229]
	global_load_dwordx4 v[214:217], v[228:229], off
	global_load_dwordx4 v[218:221], v[228:229], off offset:64
	v_add_u32_e32 v226, 176, v148
	v_lshlrev_b64 v[228:229], 7, v[226:227]
	v_lshl_add_u64 v[228:229], s[52:53], 0, v[228:229]
	v_lshl_add_u64 v[228:229], v[136:137], 4, v[228:229]
	global_load_dwordx4 v[222:225], v[228:229], off
	global_load_dwordx4 v[226:229], v[228:229], off offset:64
	s_waitcnt vmcnt(0)
	v_add_f32_e32 v166, v167, v166
	v_add_f32_e32 v168, v168, v169
	v_add_f32_e32 v166, v166, v168
	v_add_f32_e32 v170, v171, v170
	v_add_f32_e32 v172, v172, v173
	v_add_f32_e32 v170, v170, v172
	v_add_f32_e32 v166, v166, v170
	v_add_f32_e32 v174, v175, v174
	v_add_f32_e32 v176, v176, v177
	v_add_f32_e32 v174, v174, v176
	v_add_f32_e32 v178, v179, v178
	v_add_f32_e32 v180, v180, v181
	v_add_f32_e32 v178, v178, v180
	v_add_f32_e32 v174, v174, v178
	v_add_f32_e32 v182, v183, v182
	v_add_f32_e32 v184, v184, v185
	v_add_f32_e32 v182, v182, v184
	v_add_f32_e32 v186, v187, v186
	v_add_f32_e32 v188, v188, v189
	v_add_f32_e32 v186, v186, v188
	v_add_f32_e32 v182, v182, v186
	v_add_f32_e32 v190, v191, v190
	v_add_f32_e32 v192, v192, v193
	v_add_f32_e32 v190, v190, v192
	v_add_f32_e32 v194, v195, v194
	v_add_f32_e32 v196, v196, v197
	v_add_f32_e32 v194, v194, v196
	v_add_f32_e32 v190, v190, v194
	v_add_f32_e32 v198, v199, v198
	v_add_f32_e32 v200, v200, v201
	v_add_f32_e32 v198, v198, v200
	v_add_f32_e32 v202, v203, v202
	v_add_f32_e32 v204, v204, v205
	v_add_f32_e32 v202, v202, v204
	v_add_f32_e32 v198, v198, v202
	v_add_f32_e32 v206, v207, v206
	v_add_f32_e32 v208, v208, v209
	v_add_f32_e32 v206, v206, v208
	v_add_f32_e32 v210, v211, v210
	v_add_f32_e32 v212, v212, v213
	v_add_f32_e32 v210, v210, v212
	v_add_f32_e32 v206, v206, v210
	v_add_f32_e32 v214, v215, v214
	v_add_f32_e32 v216, v216, v217
	v_add_f32_e32 v214, v214, v216
	v_add_f32_e32 v218, v219, v218
	v_add_f32_e32 v220, v220, v221
	v_add_f32_e32 v218, v218, v220
	v_add_f32_e32 v214, v214, v218
	v_add_f32_e32 v222, v223, v222
	v_add_f32_e32 v224, v224, v225
	v_add_f32_e32 v222, v222, v224
	v_add_f32_e32 v226, v227, v226
	v_add_f32_e32 v228, v228, v229
	v_add_f32_e32 v226, v226, v228
	v_add_f32_e32 v222, v222, v226
	ds_bpermute_b32 v167, v153, v166
	ds_bpermute_b32 v175, v153, v174
	ds_bpermute_b32 v183, v153, v182
	ds_bpermute_b32 v191, v153, v190
	ds_bpermute_b32 v199, v153, v198
	ds_bpermute_b32 v207, v153, v206
	ds_bpermute_b32 v215, v153, v214
	ds_bpermute_b32 v223, v153, v222
	s_waitcnt lgkmcnt(0)
	v_add_f32_e32 v166, v166, v167
	v_add_f32_e32 v174, v174, v175
	v_add_f32_e32 v182, v182, v183
	v_add_f32_e32 v190, v190, v191
	v_add_f32_e32 v198, v198, v199
	v_add_f32_e32 v206, v206, v207
	v_add_f32_e32 v214, v214, v215
	v_add_f32_e32 v222, v222, v223
	ds_bpermute_b32 v167, v154, v166
	ds_bpermute_b32 v175, v154, v174
	ds_bpermute_b32 v183, v154, v182
	ds_bpermute_b32 v191, v154, v190
	ds_bpermute_b32 v199, v154, v198
	ds_bpermute_b32 v207, v154, v206
	ds_bpermute_b32 v215, v154, v214
	ds_bpermute_b32 v223, v154, v222
	s_waitcnt lgkmcnt(0)
	v_add_f32_e32 v166, v166, v167
	v_add_f32_e32 v174, v174, v175
	v_add_f32_e32 v182, v182, v183
	v_add_f32_e32 v190, v190, v191
	v_add_f32_e32 v198, v198, v199
	v_add_f32_e32 v206, v206, v207
	v_add_f32_e32 v214, v214, v215
	v_add_f32_e32 v222, v222, v223
	v_fmamk_f32 v166, v166, 0x3a000000, v158
	v_fmamk_f32 v174, v174, 0x3a000000, v158
	v_fmamk_f32 v182, v182, 0x3a000000, v158
	v_fmamk_f32 v190, v190, 0x3a000000, v158
	v_fmamk_f32 v198, v198, 0x3a000000, v158
	v_fmamk_f32 v206, v206, 0x3a000000, v158
	v_fmamk_f32 v214, v214, 0x3a000000, v158
	v_fmamk_f32 v222, v222, 0x3a000000, v158
	v_rsq_f32_e32 v166, v166
	v_rsq_f32_e32 v174, v174
	v_rsq_f32_e32 v182, v182
	v_rsq_f32_e32 v190, v190
	v_rsq_f32_e32 v198, v198
	v_rsq_f32_e32 v206, v206
	v_rsq_f32_e32 v214, v214
	v_rsq_f32_e32 v222, v222
	s_nop 0
	v_lshlrev_b64 v[146:147], 7, v[148:149]
	v_lshl_add_u64 v[146:147], s[52:53], 0, v[146:147]
	v_mov_b32_e32 v149, 0
	v_lshl_add_u64 v[146:147], v[136:137], 4, v[146:147]
	v_mov_b64_e32 v[160:161], s[50:51]
	s_waitcnt lgkmcnt(0)
	v_lshl_add_u32 v146, s68, 8, v152
	v_ashrrev_i32_e32 v147, 31, v146
	v_mad_i64_i32 v[160:161], s[68:69], v148, s82, v[160:161]
	s_waitcnt lgkmcnt(0)
	v_mov_b32_e32 v162, v166
	v_lshl_add_u64 v[160:161], v[146:147], 1, v[160:161]
	v_pk_mul_f32 v[126:127], v[126:127], v[162:163] op_sel_hi:[1,0]
	v_pk_mul_f32 v[124:125], v[124:125], v[162:163] op_sel_hi:[1,0]
	v_pk_mul_f32 v[164:165], v[122:123], v[162:163] op_sel_hi:[1,0]
	v_pk_mul_f32 v[122:123], v[120:121], v[162:163] op_sel_hi:[1,0]
	v_cvt_pk_bf16_f32 v120, v124, v125
	v_cvt_pk_bf16_f32 v121, v126, v127
	v_cvt_pk_bf16_f32 v122, v122, v123
	v_cvt_pk_bf16_f32 v123, v164, v165
	global_store_dwordx4 v[160:161], v[120:123], off
	v_pk_mul_f32 v[118:119], v[118:119], v[162:163] op_sel_hi:[1,0]
	v_pk_mul_f32 v[116:117], v[116:117], v[162:163] op_sel_hi:[1,0]
	v_pk_mul_f32 v[120:121], v[114:115], v[162:163] op_sel_hi:[1,0]
	v_pk_mul_f32 v[114:115], v[112:113], v[162:163] op_sel_hi:[1,0]
	v_cvt_pk_bf16_f32 v112, v116, v117
	v_cvt_pk_bf16_f32 v113, v118, v119
	v_cvt_pk_bf16_f32 v114, v114, v115
	v_cvt_pk_bf16_f32 v115, v120, v121
	global_store_dwordx4 v[160:161], v[112:115], off offset:256
	s_nop 1
	v_or_b32_e32 v112, 16, v148
	v_ashrrev_i32_e32 v113, 31, v112
	v_lshlrev_b64 v[114:115], 7, v[112:113]
	v_lshl_add_u64 v[114:115], s[52:53], 0, v[114:115]
	v_mov_b32_e32 v113, 0
	v_lshl_add_u64 v[114:115], v[136:137], 4, v[114:115]
	s_waitcnt lgkmcnt(0)
	v_mov_b64_e32 v[114:115], s[50:51]
	s_waitcnt lgkmcnt(0)
	v_mov_b32_e32 v116, v174
	v_mad_i64_i32 v[112:113], s[68:69], v112, s82, v[114:115]
	v_lshl_add_u64 v[112:113], v[146:147], 1, v[112:113]
	v_pk_mul_f32 v[110:111], v[110:111], v[116:117] op_sel_hi:[1,0]
	v_pk_mul_f32 v[108:109], v[108:109], v[116:117] op_sel_hi:[1,0]
	v_pk_mul_f32 v[106:107], v[106:107], v[116:117] op_sel_hi:[1,0]
	v_pk_mul_f32 v[104:105], v[104:105], v[116:117] op_sel_hi:[1,0]
	v_pk_mul_f32 v[114:115], v[102:103], v[116:117] op_sel_hi:[1,0]
	v_cvt_pk_bf16_f32 v102, v108, v109
	v_cvt_pk_bf16_f32 v103, v110, v111
	v_cvt_pk_bf16_f32 v104, v104, v105
	v_cvt_pk_bf16_f32 v105, v106, v107
	global_store_dwordx4 v[112:113], v[102:105], off
	v_pk_mul_f32 v[100:101], v[100:101], v[116:117] op_sel_hi:[1,0]
	s_nop 0
	v_pk_mul_f32 v[102:103], v[98:99], v[116:117] op_sel_hi:[1,0]
	v_pk_mul_f32 v[98:99], v[96:97], v[116:117] op_sel_hi:[1,0]
	v_cvt_pk_bf16_f32 v96, v100, v101
	v_cvt_pk_bf16_f32 v97, v114, v115
	v_cvt_pk_bf16_f32 v98, v98, v99
	v_cvt_pk_bf16_f32 v99, v102, v103
	global_store_dwordx4 v[112:113], v[96:99], off offset:256
	s_nop 1
	v_or_b32_e32 v96, 32, v148
	v_ashrrev_i32_e32 v97, 31, v96
	v_lshlrev_b64 v[98:99], 7, v[96:97]
	v_lshl_add_u64 v[98:99], s[52:53], 0, v[98:99]
	v_mov_b32_e32 v97, 0
	v_lshl_add_u64 v[98:99], v[136:137], 4, v[98:99]
	s_waitcnt lgkmcnt(0)
	v_mov_b64_e32 v[98:99], s[50:51]
	s_waitcnt lgkmcnt(0)
	v_mov_b32_e32 v100, v182
	v_mad_i64_i32 v[96:97], s[68:69], v96, s82, v[98:99]
	v_lshl_add_u64 v[96:97], v[146:147], 1, v[96:97]
	v_pk_mul_f32 v[94:95], v[94:95], v[100:101] op_sel_hi:[1,0]
	v_pk_mul_f32 v[92:93], v[92:93], v[100:101] op_sel_hi:[1,0]
	v_pk_mul_f32 v[90:91], v[90:91], v[100:101] op_sel_hi:[1,0]
	v_pk_mul_f32 v[88:89], v[88:89], v[100:101] op_sel_hi:[1,0]
	v_pk_mul_f32 v[98:99], v[86:87], v[100:101] op_sel_hi:[1,0]
	v_cvt_pk_bf16_f32 v86, v92, v93
	v_cvt_pk_bf16_f32 v87, v94, v95
	v_cvt_pk_bf16_f32 v88, v88, v89
	v_cvt_pk_bf16_f32 v89, v90, v91
	global_store_dwordx4 v[96:97], v[86:89], off
	v_pk_mul_f32 v[84:85], v[84:85], v[100:101] op_sel_hi:[1,0]
	s_nop 0
	v_pk_mul_f32 v[86:87], v[82:83], v[100:101] op_sel_hi:[1,0]
	v_pk_mul_f32 v[82:83], v[80:81], v[100:101] op_sel_hi:[1,0]
	v_cvt_pk_bf16_f32 v80, v84, v85
	v_cvt_pk_bf16_f32 v81, v98, v99
	v_cvt_pk_bf16_f32 v82, v82, v83
	v_cvt_pk_bf16_f32 v83, v86, v87
	global_store_dwordx4 v[96:97], v[80:83], off offset:256
	s_nop 1
	v_or_b32_e32 v80, 48, v148
	v_ashrrev_i32_e32 v81, 31, v80
	v_lshlrev_b64 v[82:83], 7, v[80:81]
	v_lshl_add_u64 v[82:83], s[52:53], 0, v[82:83]
	v_mov_b32_e32 v81, 0
	v_lshl_add_u64 v[82:83], v[136:137], 4, v[82:83]
	s_waitcnt lgkmcnt(0)
	v_mov_b64_e32 v[82:83], s[50:51]
	s_waitcnt lgkmcnt(0)
	v_mov_b32_e32 v84, v190
	v_mad_i64_i32 v[80:81], s[68:69], v80, s82, v[82:83]
	v_lshl_add_u64 v[80:81], v[146:147], 1, v[80:81]
	v_pk_mul_f32 v[78:79], v[78:79], v[84:85] op_sel_hi:[1,0]
	v_pk_mul_f32 v[76:77], v[76:77], v[84:85] op_sel_hi:[1,0]
	v_pk_mul_f32 v[74:75], v[74:75], v[84:85] op_sel_hi:[1,0]
	v_pk_mul_f32 v[72:73], v[72:73], v[84:85] op_sel_hi:[1,0]
	v_pk_mul_f32 v[82:83], v[70:71], v[84:85] op_sel_hi:[1,0]
	v_cvt_pk_bf16_f32 v70, v76, v77
	v_cvt_pk_bf16_f32 v71, v78, v79
	v_cvt_pk_bf16_f32 v72, v72, v73
	v_cvt_pk_bf16_f32 v73, v74, v75
	global_store_dwordx4 v[80:81], v[70:73], off
	v_pk_mul_f32 v[68:69], v[68:69], v[84:85] op_sel_hi:[1,0]
	s_nop 0
	v_pk_mul_f32 v[70:71], v[66:67], v[84:85] op_sel_hi:[1,0]
	v_pk_mul_f32 v[66:67], v[64:65], v[84:85] op_sel_hi:[1,0]
	v_cvt_pk_bf16_f32 v64, v68, v69
	v_cvt_pk_bf16_f32 v65, v82, v83
	v_cvt_pk_bf16_f32 v66, v66, v67
	v_cvt_pk_bf16_f32 v67, v70, v71
	global_store_dwordx4 v[80:81], v[64:67], off offset:256
	s_nop 1
	v_add_u32_e32 v64, 0x80, v148
	v_ashrrev_i32_e32 v65, 31, v64
	v_lshlrev_b64 v[66:67], 7, v[64:65]
	v_lshl_add_u64 v[66:67], s[52:53], 0, v[66:67]
	v_mov_b32_e32 v65, 0
	v_lshl_add_u64 v[66:67], v[136:137], 4, v[66:67]
	s_waitcnt lgkmcnt(0)
	v_mov_b64_e32 v[66:67], s[50:51]
	s_waitcnt lgkmcnt(0)
	v_mov_b32_e32 v68, v198
	v_mad_i64_i32 v[64:65], s[68:69], v64, s82, v[66:67]
	v_lshl_add_u64 v[64:65], v[146:147], 1, v[64:65]
	v_pk_mul_f32 v[62:63], v[62:63], v[68:69] op_sel_hi:[1,0]
	v_pk_mul_f32 v[60:61], v[60:61], v[68:69] op_sel_hi:[1,0]
	v_pk_mul_f32 v[58:59], v[58:59], v[68:69] op_sel_hi:[1,0]
	v_pk_mul_f32 v[56:57], v[56:57], v[68:69] op_sel_hi:[1,0]
	v_pk_mul_f32 v[66:67], v[54:55], v[68:69] op_sel_hi:[1,0]
	v_cvt_pk_bf16_f32 v54, v60, v61
	v_cvt_pk_bf16_f32 v55, v62, v63
	v_cvt_pk_bf16_f32 v56, v56, v57
	v_cvt_pk_bf16_f32 v57, v58, v59
	global_store_dwordx4 v[64:65], v[54:57], off
	v_pk_mul_f32 v[52:53], v[52:53], v[68:69] op_sel_hi:[1,0]
	s_nop 0
	v_pk_mul_f32 v[54:55], v[50:51], v[68:69] op_sel_hi:[1,0]
	v_pk_mul_f32 v[50:51], v[48:49], v[68:69] op_sel_hi:[1,0]
	v_cvt_pk_bf16_f32 v48, v52, v53
	v_cvt_pk_bf16_f32 v49, v66, v67
	v_cvt_pk_bf16_f32 v50, v50, v51
	v_cvt_pk_bf16_f32 v51, v54, v55
	global_store_dwordx4 v[64:65], v[48:51], off offset:256
	s_nop 1
	v_add_u32_e32 v48, 0x90, v148
	v_ashrrev_i32_e32 v49, 31, v48
	v_lshlrev_b64 v[50:51], 7, v[48:49]
	v_lshl_add_u64 v[50:51], s[52:53], 0, v[50:51]
	v_mov_b32_e32 v49, 0
	v_lshl_add_u64 v[50:51], v[136:137], 4, v[50:51]
	s_waitcnt lgkmcnt(0)
	v_mov_b64_e32 v[50:51], s[50:51]
	s_waitcnt lgkmcnt(0)
	v_mov_b32_e32 v52, v206
	v_mad_i64_i32 v[48:49], s[68:69], v48, s82, v[50:51]
	v_lshl_add_u64 v[48:49], v[146:147], 1, v[48:49]
	v_pk_mul_f32 v[46:47], v[46:47], v[52:53] op_sel_hi:[1,0]
	v_pk_mul_f32 v[44:45], v[44:45], v[52:53] op_sel_hi:[1,0]
	v_pk_mul_f32 v[42:43], v[42:43], v[52:53] op_sel_hi:[1,0]
	v_pk_mul_f32 v[40:41], v[40:41], v[52:53] op_sel_hi:[1,0]
	v_pk_mul_f32 v[50:51], v[38:39], v[52:53] op_sel_hi:[1,0]
	v_cvt_pk_bf16_f32 v38, v44, v45
	v_cvt_pk_bf16_f32 v39, v46, v47
	v_cvt_pk_bf16_f32 v40, v40, v41
	v_cvt_pk_bf16_f32 v41, v42, v43
	global_store_dwordx4 v[48:49], v[38:41], off
	v_pk_mul_f32 v[36:37], v[36:37], v[52:53] op_sel_hi:[1,0]
	s_nop 0
	v_pk_mul_f32 v[38:39], v[34:35], v[52:53] op_sel_hi:[1,0]
	v_pk_mul_f32 v[34:35], v[32:33], v[52:53] op_sel_hi:[1,0]
	v_cvt_pk_bf16_f32 v32, v36, v37
	v_cvt_pk_bf16_f32 v33, v50, v51
	v_cvt_pk_bf16_f32 v34, v34, v35
	v_cvt_pk_bf16_f32 v35, v38, v39
	global_store_dwordx4 v[48:49], v[32:35], off offset:256
	s_nop 1
	v_add_u32_e32 v32, 0xa0, v148
	v_ashrrev_i32_e32 v33, 31, v32
	v_lshlrev_b64 v[34:35], 7, v[32:33]
	v_lshl_add_u64 v[34:35], s[52:53], 0, v[34:35]
	v_mov_b32_e32 v33, 0
	v_lshl_add_u64 v[34:35], v[136:137], 4, v[34:35]
	s_waitcnt lgkmcnt(0)
	v_mov_b64_e32 v[34:35], s[50:51]
	s_waitcnt lgkmcnt(0)
	v_mov_b32_e32 v36, v214
	v_mad_i64_i32 v[32:33], s[68:69], v32, s82, v[34:35]
	v_lshl_add_u64 v[32:33], v[146:147], 1, v[32:33]
	v_pk_mul_f32 v[30:31], v[30:31], v[36:37] op_sel_hi:[1,0]
	v_pk_mul_f32 v[28:29], v[28:29], v[36:37] op_sel_hi:[1,0]
	v_pk_mul_f32 v[26:27], v[26:27], v[36:37] op_sel_hi:[1,0]
	v_pk_mul_f32 v[24:25], v[24:25], v[36:37] op_sel_hi:[1,0]
	v_pk_mul_f32 v[34:35], v[22:23], v[36:37] op_sel_hi:[1,0]
	v_cvt_pk_bf16_f32 v22, v28, v29
	v_cvt_pk_bf16_f32 v23, v30, v31
	v_cvt_pk_bf16_f32 v24, v24, v25
	v_cvt_pk_bf16_f32 v25, v26, v27
	global_store_dwordx4 v[32:33], v[22:25], off
	v_pk_mul_f32 v[20:21], v[20:21], v[36:37] op_sel_hi:[1,0]
	s_nop 0
	v_pk_mul_f32 v[22:23], v[18:19], v[36:37] op_sel_hi:[1,0]
	v_pk_mul_f32 v[18:19], v[16:17], v[36:37] op_sel_hi:[1,0]
	v_cvt_pk_bf16_f32 v16, v20, v21
	v_cvt_pk_bf16_f32 v17, v34, v35
	v_cvt_pk_bf16_f32 v18, v18, v19
	v_cvt_pk_bf16_f32 v19, v22, v23
	global_store_dwordx4 v[32:33], v[16:19], off offset:256
	s_nop 1
	v_add_u32_e32 v16, 0xb0, v148
	v_ashrrev_i32_e32 v17, 31, v16
	v_lshlrev_b64 v[18:19], 7, v[16:17]
	v_lshl_add_u64 v[18:19], s[52:53], 0, v[18:19]
	v_mov_b32_e32 v17, 0
	v_lshl_add_u64 v[18:19], v[136:137], 4, v[18:19]
	s_andn2_b64 vcc, exec, s[12:13]
	s_mov_b64 s[12:13], -1
	s_waitcnt lgkmcnt(0)
	v_mov_b64_e32 v[18:19], s[50:51]
	s_waitcnt lgkmcnt(0)
	v_mov_b32_e32 v20, v222
	v_mad_i64_i32 v[16:17], s[68:69], v16, s82, v[18:19]
	v_lshl_add_u64 v[16:17], v[146:147], 1, v[16:17]
	v_pk_mul_f32 v[14:15], v[14:15], v[20:21] op_sel_hi:[1,0]
	v_pk_mul_f32 v[12:13], v[12:13], v[20:21] op_sel_hi:[1,0]
	v_pk_mul_f32 v[10:11], v[10:11], v[20:21] op_sel_hi:[1,0]
	v_pk_mul_f32 v[8:9], v[8:9], v[20:21] op_sel_hi:[1,0]
	v_pk_mul_f32 v[18:19], v[6:7], v[20:21] op_sel_hi:[1,0]
	v_cvt_pk_bf16_f32 v6, v12, v13
	v_cvt_pk_bf16_f32 v7, v14, v15
	v_cvt_pk_bf16_f32 v8, v8, v9
	v_cvt_pk_bf16_f32 v9, v10, v11
	global_store_dwordx4 v[16:17], v[6:9], off
	v_pk_mul_f32 v[4:5], v[4:5], v[20:21] op_sel_hi:[1,0]
	s_nop 0
	v_pk_mul_f32 v[6:7], v[2:3], v[20:21] op_sel_hi:[1,0]
	v_pk_mul_f32 v[2:3], v[0:1], v[20:21] op_sel_hi:[1,0]
	v_cvt_pk_bf16_f32 v0, v4, v5
	v_cvt_pk_bf16_f32 v1, v18, v19
	v_cvt_pk_bf16_f32 v2, v2, v3
	v_cvt_pk_bf16_f32 v3, v6, v7
	global_store_dwordx4 v[16:17], v[0:3], off offset:256
	s_cbranch_vccnz .LBB0_845
	s_andn2_b64 vcc, exec, s[16:17]
	s_cbranch_vccnz .LBB0_844
	s_barrier
	s_branch .LBB0_844

.LBB0_1788:
	v_lshl_add_u32 v148, s70, 8, v150
	v_ashrrev_i32_e32 v149, 31, v148
	v_mov_b32_e32 v227, 0
	v_mov_b32_e32 v226, v148
	v_lshlrev_b64 v[228:229], 7, v[226:227]
	v_lshl_add_u64 v[228:229], s[52:53], 0, v[228:229]
	v_lshl_add_u64 v[228:229], v[136:137], 4, v[228:229]
	global_load_dwordx4 v[166:169], v[228:229], off
	global_load_dwordx4 v[170:173], v[228:229], off offset:64
	v_add_u32_e32 v226, 16, v148
	v_lshlrev_b64 v[228:229], 7, v[226:227]
	v_lshl_add_u64 v[228:229], s[52:53], 0, v[228:229]
	v_lshl_add_u64 v[228:229], v[136:137], 4, v[228:229]
	global_load_dwordx4 v[174:177], v[228:229], off
	global_load_dwordx4 v[178:181], v[228:229], off offset:64
	v_add_u32_e32 v226, 32, v148
	v_lshlrev_b64 v[228:229], 7, v[226:227]
	v_lshl_add_u64 v[228:229], s[52:53], 0, v[228:229]
	v_lshl_add_u64 v[228:229], v[136:137], 4, v[228:229]
	global_load_dwordx4 v[182:185], v[228:229], off
	global_load_dwordx4 v[186:189], v[228:229], off offset:64
	v_add_u32_e32 v226, 48, v148
	v_lshlrev_b64 v[228:229], 7, v[226:227]
	v_lshl_add_u64 v[228:229], s[52:53], 0, v[228:229]
	v_lshl_add_u64 v[228:229], v[136:137], 4, v[228:229]
	global_load_dwordx4 v[190:193], v[228:229], off
	global_load_dwordx4 v[194:197], v[228:229], off offset:64
	v_add_u32_e32 v226, 128, v148
	v_lshlrev_b64 v[228:229], 7, v[226:227]
	v_lshl_add_u64 v[228:229], s[52:53], 0, v[228:229]
	v_lshl_add_u64 v[228:229], v[136:137], 4, v[228:229]
	global_load_dwordx4 v[198:201], v[228:229], off
	global_load_dwordx4 v[202:205], v[228:229], off offset:64
	v_add_u32_e32 v226, 144, v148
	v_lshlrev_b64 v[228:229], 7, v[226:227]
	v_lshl_add_u64 v[228:229], s[52:53], 0, v[228:229]
	v_lshl_add_u64 v[228:229], v[136:137], 4, v[228:229]
	global_load_dwordx4 v[206:209], v[228:229], off
	global_load_dwordx4 v[210:213], v[228:229], off offset:64
	v_add_u32_e32 v226, 160, v148
	v_lshlrev_b64 v[228:229], 7, v[226:227]
	v_lshl_add_u64 v[228:229], s[52:53], 0, v[228:229]
	v_lshl_add_u64 v[228:229], v[136:137], 4, v[228:229]
	global_load_dwordx4 v[214:217], v[228:229], off
	global_load_dwordx4 v[218:221], v[228:229], off offset:64
	v_add_u32_e32 v226, 176, v148
	v_lshlrev_b64 v[228:229], 7, v[226:227]
	v_lshl_add_u64 v[228:229], s[52:53], 0, v[228:229]
	v_lshl_add_u64 v[228:229], v[136:137], 4, v[228:229]
	global_load_dwordx4 v[222:225], v[228:229], off
	global_load_dwordx4 v[226:229], v[228:229], off offset:64
	s_waitcnt vmcnt(0)
	v_add_f32_e32 v166, v167, v166
	v_add_f32_e32 v168, v168, v169
	v_add_f32_e32 v166, v166, v168
	v_add_f32_e32 v170, v171, v170
	v_add_f32_e32 v172, v172, v173
	v_add_f32_e32 v170, v170, v172
	v_add_f32_e32 v166, v166, v170
	v_add_f32_e32 v174, v175, v174
	v_add_f32_e32 v176, v176, v177
	v_add_f32_e32 v174, v174, v176
	v_add_f32_e32 v178, v179, v178
	v_add_f32_e32 v180, v180, v181
	v_add_f32_e32 v178, v178, v180
	v_add_f32_e32 v174, v174, v178
	v_add_f32_e32 v182, v183, v182
	v_add_f32_e32 v184, v184, v185
	v_add_f32_e32 v182, v182, v184
	v_add_f32_e32 v186, v187, v186
	v_add_f32_e32 v188, v188, v189
	v_add_f32_e32 v186, v186, v188
	v_add_f32_e32 v182, v182, v186
	v_add_f32_e32 v190, v191, v190
	v_add_f32_e32 v192, v192, v193
	v_add_f32_e32 v190, v190, v192
	v_add_f32_e32 v194, v195, v194
	v_add_f32_e32 v196, v196, v197
	v_add_f32_e32 v194, v194, v196
	v_add_f32_e32 v190, v190, v194
	v_add_f32_e32 v198, v199, v198
	v_add_f32_e32 v200, v200, v201
	v_add_f32_e32 v198, v198, v200
	v_add_f32_e32 v202, v203, v202
	v_add_f32_e32 v204, v204, v205
	v_add_f32_e32 v202, v202, v204
	v_add_f32_e32 v198, v198, v202
	v_add_f32_e32 v206, v207, v206
	v_add_f32_e32 v208, v208, v209
	v_add_f32_e32 v206, v206, v208
	v_add_f32_e32 v210, v211, v210
	v_add_f32_e32 v212, v212, v213
	v_add_f32_e32 v210, v210, v212
	v_add_f32_e32 v206, v206, v210
	v_add_f32_e32 v214, v215, v214
	v_add_f32_e32 v216, v216, v217
	v_add_f32_e32 v214, v214, v216
	v_add_f32_e32 v218, v219, v218
	v_add_f32_e32 v220, v220, v221
	v_add_f32_e32 v218, v218, v220
	v_add_f32_e32 v214, v214, v218
	v_add_f32_e32 v222, v223, v222
	v_add_f32_e32 v224, v224, v225
	v_add_f32_e32 v222, v222, v224
	v_add_f32_e32 v226, v227, v226
	v_add_f32_e32 v228, v228, v229
	v_add_f32_e32 v226, v226, v228
	v_add_f32_e32 v222, v222, v226
	ds_bpermute_b32 v167, v153, v166
	ds_bpermute_b32 v175, v153, v174
	ds_bpermute_b32 v183, v153, v182
	ds_bpermute_b32 v191, v153, v190
	ds_bpermute_b32 v199, v153, v198
	ds_bpermute_b32 v207, v153, v206
	ds_bpermute_b32 v215, v153, v214
	ds_bpermute_b32 v223, v153, v222
	s_waitcnt lgkmcnt(0)
	v_add_f32_e32 v166, v166, v167
	v_add_f32_e32 v174, v174, v175
	v_add_f32_e32 v182, v182, v183
	v_add_f32_e32 v190, v190, v191
	v_add_f32_e32 v198, v198, v199
	v_add_f32_e32 v206, v206, v207
	v_add_f32_e32 v214, v214, v215
	v_add_f32_e32 v222, v222, v223
	ds_bpermute_b32 v167, v154, v166
	ds_bpermute_b32 v175, v154, v174
	ds_bpermute_b32 v183, v154, v182
	ds_bpermute_b32 v191, v154, v190
	ds_bpermute_b32 v199, v154, v198
	ds_bpermute_b32 v207, v154, v206
	ds_bpermute_b32 v215, v154, v214
	ds_bpermute_b32 v223, v154, v222
	s_waitcnt lgkmcnt(0)
	v_add_f32_e32 v166, v166, v167
	v_add_f32_e32 v174, v174, v175
	v_add_f32_e32 v182, v182, v183
	v_add_f32_e32 v190, v190, v191
	v_add_f32_e32 v198, v198, v199
	v_add_f32_e32 v206, v206, v207
	v_add_f32_e32 v214, v214, v215
	v_add_f32_e32 v222, v222, v223
	v_fmamk_f32 v166, v166, 0x3a000000, v158
	v_fmamk_f32 v174, v174, 0x3a000000, v158
	v_fmamk_f32 v182, v182, 0x3a000000, v158
	v_fmamk_f32 v190, v190, 0x3a000000, v158
	v_fmamk_f32 v198, v198, 0x3a000000, v158
	v_fmamk_f32 v206, v206, 0x3a000000, v158
	v_fmamk_f32 v214, v214, 0x3a000000, v158
	v_fmamk_f32 v222, v222, 0x3a000000, v158
	v_rsq_f32_e32 v166, v166
	v_rsq_f32_e32 v174, v174
	v_rsq_f32_e32 v182, v182
	v_rsq_f32_e32 v190, v190
	v_rsq_f32_e32 v198, v198
	v_rsq_f32_e32 v206, v206
	v_rsq_f32_e32 v214, v214
	v_rsq_f32_e32 v222, v222
	s_nop 0
	v_lshlrev_b64 v[146:147], 7, v[148:149]
	v_lshl_add_u64 v[146:147], s[52:53], 0, v[146:147]
	v_mov_b32_e32 v159, 0
	v_lshl_add_u64 v[146:147], v[136:137], 4, v[146:147]
	v_lshlrev_b64 v[160:161], 14, v[148:149]
	v_lshl_add_u64 v[160:161], s[50:51], 0, v[160:161]
	s_waitcnt lgkmcnt(0)
	v_lshl_add_u32 v146, s68, 8, v152
	s_waitcnt lgkmcnt(0)
	v_mov_b32_e32 v162, v166
	v_ashrrev_i32_e32 v147, 31, v146
	v_lshl_add_u64 v[160:161], v[146:147], 1, v[160:161]
	v_pk_mul_f32 v[120:121], v[120:121], v[162:163] op_sel_hi:[1,0]
	v_pk_mul_f32 v[124:125], v[124:125], v[162:163] op_sel_hi:[1,0]
	v_max_f32_e32 v120, 0, v120
	v_pk_mul_f32 v[126:127], v[126:127], v[162:163] op_sel_hi:[1,0]
	v_pk_mul_f32 v[122:123], v[122:123], v[162:163] op_sel_hi:[1,0]
	v_max_f32_e32 v125, 0, v125
	v_mul_f32_e32 v149, v120, v120
	v_max_f32_e32 v120, 0, v121
	v_mul_f32_e32 v121, v125, v125
	v_mul_f32_e32 v125, v120, v120
	v_max_f32_e32 v120, 0, v126
	v_max_f32_e32 v122, 0, v122
	v_max_f32_e32 v124, 0, v124
	v_mul_f32_e32 v126, v120, v120
	v_mul_f32_e32 v159, v122, v122
	v_max_f32_e32 v120, 0, v127
	v_max_f32_e32 v122, 0, v123
	v_mul_f32_e32 v124, v124, v124
	v_mul_f32_e32 v123, v120, v120
	v_mul_f32_e32 v127, v122, v122
	v_pk_mul_f32 v[114:115], v[114:115], v[162:163] op_sel_hi:[1,0]
	v_pk_mul_f32 v[112:113], v[112:113], v[162:163] op_sel_hi:[1,0]
	v_cvt_pk_bf16_f32 v120, v124, v121
	v_cvt_pk_bf16_f32 v121, v126, v123
	v_cvt_pk_bf16_f32 v122, v149, v125
	v_cvt_pk_bf16_f32 v123, v159, v127
	v_pk_mul_f32 v[118:119], v[118:119], v[162:163] op_sel_hi:[1,0]
	v_pk_mul_f32 v[116:117], v[116:117], v[162:163] op_sel_hi:[1,0]
	v_max_f32_e32 v112, 0, v112
	v_max_f32_e32 v113, 0, v113
	v_max_f32_e32 v114, 0, v114
	global_store_dwordx4 v[160:161], v[120:123], off
	v_max_f32_e32 v116, 0, v116
	v_max_f32_e32 v115, 0, v115
	v_mul_f32_e32 v120, v112, v112
	v_max_f32_e32 v112, 0, v117
	v_mul_f32_e32 v117, v113, v113
	v_max_f32_e32 v113, 0, v118
	v_mul_f32_e32 v118, v114, v114
	v_max_f32_e32 v114, 0, v119
	v_mul_f32_e32 v116, v116, v116
	v_mul_f32_e32 v112, v112, v112
	v_mul_f32_e32 v113, v113, v113
	v_mul_f32_e32 v114, v114, v114
	v_mul_f32_e32 v115, v115, v115
	v_cvt_pk_bf16_f32 v112, v116, v112
	v_cvt_pk_bf16_f32 v113, v113, v114
	v_cvt_pk_bf16_f32 v114, v120, v117
	v_cvt_pk_bf16_f32 v115, v118, v115
	global_store_dwordx4 v[160:161], v[112:115], off offset:256
	v_mov_b32_e32 v116, 0
	s_nop 0
	v_or_b32_e32 v112, 16, v148
	v_ashrrev_i32_e32 v113, 31, v112
	v_lshlrev_b64 v[114:115], 7, v[112:113]
	v_lshl_add_u64 v[114:115], s[52:53], 0, v[114:115]
	v_lshl_add_u64 v[114:115], v[136:137], 4, v[114:115]
	v_lshlrev_b64 v[112:113], 14, v[112:113]
	v_lshl_add_u64 v[112:113], s[50:51], 0, v[112:113]
	v_lshl_add_u64 v[112:113], v[146:147], 1, v[112:113]
	s_waitcnt lgkmcnt(0)
	s_waitcnt lgkmcnt(0)
	v_mov_b32_e32 v114, v174
	s_nop 0
	v_pk_mul_f32 v[108:109], v[108:109], v[114:115] op_sel_hi:[1,0]
	v_pk_mul_f32 v[106:107], v[106:107], v[114:115] op_sel_hi:[1,0]
	v_pk_mul_f32 v[104:105], v[104:105], v[114:115] op_sel_hi:[1,0]
	v_pk_mul_f32 v[110:111], v[110:111], v[114:115] op_sel_hi:[1,0]
	v_max_f32_e32 v104, 0, v104
	v_max_f32_e32 v109, 0, v109
	v_max_f32_e32 v105, 0, v105
	v_max_f32_e32 v106, 0, v106
	v_max_f32_e32 v108, 0, v108
	v_mul_f32_e32 v115, v104, v104
	v_mul_f32_e32 v104, v109, v109
	v_mul_f32_e32 v109, v105, v105
	v_max_f32_e32 v105, 0, v110
	v_mul_f32_e32 v110, v106, v106
	v_max_f32_e32 v106, 0, v111
	v_max_f32_e32 v107, 0, v107
	v_mul_f32_e32 v108, v108, v108
	v_mul_f32_e32 v105, v105, v105
	v_mul_f32_e32 v106, v106, v106
	v_mul_f32_e32 v107, v107, v107
	v_pk_mul_f32 v[98:99], v[98:99], v[114:115] op_sel_hi:[1,0]
	v_pk_mul_f32 v[96:97], v[96:97], v[114:115] op_sel_hi:[1,0]
	v_cvt_pk_bf16_f32 v104, v108, v104
	v_cvt_pk_bf16_f32 v105, v105, v106
	v_cvt_pk_bf16_f32 v106, v115, v109
	v_cvt_pk_bf16_f32 v107, v110, v107
	v_pk_mul_f32 v[102:103], v[102:103], v[114:115] op_sel_hi:[1,0]
	v_pk_mul_f32 v[100:101], v[100:101], v[114:115] op_sel_hi:[1,0]
	v_max_f32_e32 v96, 0, v96
	v_max_f32_e32 v97, 0, v97
	v_max_f32_e32 v98, 0, v98
	global_store_dwordx4 v[112:113], v[104:107], off
	v_max_f32_e32 v100, 0, v100
	v_max_f32_e32 v99, 0, v99
	v_mul_f32_e32 v104, v96, v96
	v_max_f32_e32 v96, 0, v101
	v_mul_f32_e32 v101, v97, v97
	v_max_f32_e32 v97, 0, v102
	v_mul_f32_e32 v102, v98, v98
	v_max_f32_e32 v98, 0, v103
	v_mul_f32_e32 v100, v100, v100
	v_mul_f32_e32 v96, v96, v96
	v_mul_f32_e32 v97, v97, v97
	v_mul_f32_e32 v98, v98, v98
	v_mul_f32_e32 v99, v99, v99
	v_cvt_pk_bf16_f32 v96, v100, v96
	v_cvt_pk_bf16_f32 v97, v97, v98
	v_cvt_pk_bf16_f32 v98, v104, v101
	v_cvt_pk_bf16_f32 v99, v102, v99
	global_store_dwordx4 v[112:113], v[96:99], off offset:256
	v_mov_b32_e32 v100, 0
	s_nop 0
	v_or_b32_e32 v96, 32, v148
	v_ashrrev_i32_e32 v97, 31, v96
	v_lshlrev_b64 v[98:99], 7, v[96:97]
	v_lshl_add_u64 v[98:99], s[52:53], 0, v[98:99]
	v_lshl_add_u64 v[98:99], v[136:137], 4, v[98:99]
	v_lshlrev_b64 v[96:97], 14, v[96:97]
	v_lshl_add_u64 v[96:97], s[50:51], 0, v[96:97]
	v_lshl_add_u64 v[96:97], v[146:147], 1, v[96:97]
	s_waitcnt lgkmcnt(0)
	s_waitcnt lgkmcnt(0)
	v_mov_b32_e32 v98, v182
	s_nop 0
	v_pk_mul_f32 v[92:93], v[92:93], v[98:99] op_sel_hi:[1,0]
	v_pk_mul_f32 v[90:91], v[90:91], v[98:99] op_sel_hi:[1,0]
	v_pk_mul_f32 v[88:89], v[88:89], v[98:99] op_sel_hi:[1,0]
	v_pk_mul_f32 v[94:95], v[94:95], v[98:99] op_sel_hi:[1,0]
	v_max_f32_e32 v88, 0, v88
	v_max_f32_e32 v93, 0, v93
	v_max_f32_e32 v89, 0, v89
	v_max_f32_e32 v90, 0, v90
	v_max_f32_e32 v92, 0, v92
	v_mul_f32_e32 v99, v88, v88
	v_mul_f32_e32 v88, v93, v93
	v_mul_f32_e32 v93, v89, v89
	v_max_f32_e32 v89, 0, v94
	v_mul_f32_e32 v94, v90, v90
	v_max_f32_e32 v90, 0, v95
	v_max_f32_e32 v91, 0, v91
	v_mul_f32_e32 v92, v92, v92
	v_mul_f32_e32 v89, v89, v89
	v_mul_f32_e32 v90, v90, v90
	v_mul_f32_e32 v91, v91, v91
	v_pk_mul_f32 v[82:83], v[82:83], v[98:99] op_sel_hi:[1,0]
	v_pk_mul_f32 v[80:81], v[80:81], v[98:99] op_sel_hi:[1,0]
	v_cvt_pk_bf16_f32 v88, v92, v88
	v_cvt_pk_bf16_f32 v89, v89, v90
	v_cvt_pk_bf16_f32 v90, v99, v93
	v_cvt_pk_bf16_f32 v91, v94, v91
	v_pk_mul_f32 v[86:87], v[86:87], v[98:99] op_sel_hi:[1,0]
	v_pk_mul_f32 v[84:85], v[84:85], v[98:99] op_sel_hi:[1,0]
	v_max_f32_e32 v80, 0, v80
	v_max_f32_e32 v81, 0, v81
	v_max_f32_e32 v82, 0, v82
	global_store_dwordx4 v[96:97], v[88:91], off
	v_max_f32_e32 v84, 0, v84
	v_max_f32_e32 v83, 0, v83
	v_mul_f32_e32 v88, v80, v80
	v_max_f32_e32 v80, 0, v85
	v_mul_f32_e32 v85, v81, v81
	v_max_f32_e32 v81, 0, v86
	v_mul_f32_e32 v86, v82, v82
	v_max_f32_e32 v82, 0, v87
	v_mul_f32_e32 v84, v84, v84
	v_mul_f32_e32 v80, v80, v80
	v_mul_f32_e32 v81, v81, v81
	v_mul_f32_e32 v82, v82, v82
	v_mul_f32_e32 v83, v83, v83
	v_cvt_pk_bf16_f32 v80, v84, v80
	v_cvt_pk_bf16_f32 v81, v81, v82
	v_cvt_pk_bf16_f32 v82, v88, v85
	v_cvt_pk_bf16_f32 v83, v86, v83
	global_store_dwordx4 v[96:97], v[80:83], off offset:256
	v_mov_b32_e32 v84, 0
	s_nop 0
	v_or_b32_e32 v80, 48, v148
	v_ashrrev_i32_e32 v81, 31, v80
	v_lshlrev_b64 v[82:83], 7, v[80:81]
	v_lshl_add_u64 v[82:83], s[52:53], 0, v[82:83]
	v_lshl_add_u64 v[82:83], v[136:137], 4, v[82:83]
	v_lshlrev_b64 v[80:81], 14, v[80:81]
	v_lshl_add_u64 v[80:81], s[50:51], 0, v[80:81]
	v_lshl_add_u64 v[80:81], v[146:147], 1, v[80:81]
	s_waitcnt lgkmcnt(0)
	s_waitcnt lgkmcnt(0)
	v_mov_b32_e32 v82, v190
	s_nop 0
	v_pk_mul_f32 v[76:77], v[76:77], v[82:83] op_sel_hi:[1,0]
	v_pk_mul_f32 v[74:75], v[74:75], v[82:83] op_sel_hi:[1,0]
	v_pk_mul_f32 v[72:73], v[72:73], v[82:83] op_sel_hi:[1,0]
	v_pk_mul_f32 v[78:79], v[78:79], v[82:83] op_sel_hi:[1,0]
	v_max_f32_e32 v72, 0, v72
	v_max_f32_e32 v77, 0, v77
	v_max_f32_e32 v73, 0, v73
	v_max_f32_e32 v74, 0, v74
	v_max_f32_e32 v76, 0, v76
	v_mul_f32_e32 v83, v72, v72
	v_mul_f32_e32 v72, v77, v77
	v_mul_f32_e32 v77, v73, v73
	v_max_f32_e32 v73, 0, v78
	v_mul_f32_e32 v78, v74, v74
	v_max_f32_e32 v74, 0, v79
	v_max_f32_e32 v75, 0, v75
	v_mul_f32_e32 v76, v76, v76
	v_mul_f32_e32 v73, v73, v73
	v_mul_f32_e32 v74, v74, v74
	v_mul_f32_e32 v75, v75, v75
	v_pk_mul_f32 v[66:67], v[66:67], v[82:83] op_sel_hi:[1,0]
	v_pk_mul_f32 v[64:65], v[64:65], v[82:83] op_sel_hi:[1,0]
	v_cvt_pk_bf16_f32 v72, v76, v72
	v_cvt_pk_bf16_f32 v73, v73, v74
	v_cvt_pk_bf16_f32 v74, v83, v77
	v_cvt_pk_bf16_f32 v75, v78, v75
	v_pk_mul_f32 v[70:71], v[70:71], v[82:83] op_sel_hi:[1,0]
	v_pk_mul_f32 v[68:69], v[68:69], v[82:83] op_sel_hi:[1,0]
	v_max_f32_e32 v64, 0, v64
	v_max_f32_e32 v65, 0, v65
	v_max_f32_e32 v66, 0, v66
	global_store_dwordx4 v[80:81], v[72:75], off
	v_max_f32_e32 v68, 0, v68
	v_max_f32_e32 v67, 0, v67
	v_mul_f32_e32 v72, v64, v64
	v_max_f32_e32 v64, 0, v69
	v_mul_f32_e32 v69, v65, v65
	v_max_f32_e32 v65, 0, v70
	v_mul_f32_e32 v70, v66, v66
	v_max_f32_e32 v66, 0, v71
	v_mul_f32_e32 v68, v68, v68
	v_mul_f32_e32 v64, v64, v64
	v_mul_f32_e32 v65, v65, v65
	v_mul_f32_e32 v66, v66, v66
	v_mul_f32_e32 v67, v67, v67
	v_cvt_pk_bf16_f32 v64, v68, v64
	v_cvt_pk_bf16_f32 v65, v65, v66
	v_cvt_pk_bf16_f32 v66, v72, v69
	v_cvt_pk_bf16_f32 v67, v70, v67
	global_store_dwordx4 v[80:81], v[64:67], off offset:256
	v_mov_b32_e32 v68, 0
	s_nop 0
	v_add_u32_e32 v64, 0x80, v148
	v_ashrrev_i32_e32 v65, 31, v64
	v_lshlrev_b64 v[66:67], 7, v[64:65]
	v_lshl_add_u64 v[66:67], s[52:53], 0, v[66:67]
	v_lshl_add_u64 v[66:67], v[136:137], 4, v[66:67]
	v_lshlrev_b64 v[64:65], 14, v[64:65]
	v_lshl_add_u64 v[64:65], s[50:51], 0, v[64:65]
	v_lshl_add_u64 v[64:65], v[146:147], 1, v[64:65]
	s_waitcnt lgkmcnt(0)
	s_waitcnt lgkmcnt(0)
	v_mov_b32_e32 v66, v198
	s_nop 0
	v_pk_mul_f32 v[60:61], v[60:61], v[66:67] op_sel_hi:[1,0]
	v_pk_mul_f32 v[58:59], v[58:59], v[66:67] op_sel_hi:[1,0]
	v_pk_mul_f32 v[56:57], v[56:57], v[66:67] op_sel_hi:[1,0]
	v_pk_mul_f32 v[62:63], v[62:63], v[66:67] op_sel_hi:[1,0]
	v_max_f32_e32 v56, 0, v56
	v_max_f32_e32 v61, 0, v61
	v_max_f32_e32 v57, 0, v57
	v_max_f32_e32 v58, 0, v58
	v_max_f32_e32 v60, 0, v60
	v_mul_f32_e32 v67, v56, v56
	v_mul_f32_e32 v56, v61, v61
	v_mul_f32_e32 v61, v57, v57
	v_max_f32_e32 v57, 0, v62
	v_mul_f32_e32 v62, v58, v58
	v_max_f32_e32 v58, 0, v63
	v_max_f32_e32 v59, 0, v59
	v_mul_f32_e32 v60, v60, v60
	v_mul_f32_e32 v57, v57, v57
	v_mul_f32_e32 v58, v58, v58
	v_mul_f32_e32 v59, v59, v59
	v_pk_mul_f32 v[50:51], v[50:51], v[66:67] op_sel_hi:[1,0]
	v_pk_mul_f32 v[48:49], v[48:49], v[66:67] op_sel_hi:[1,0]
	v_cvt_pk_bf16_f32 v56, v60, v56
	v_cvt_pk_bf16_f32 v57, v57, v58
	v_cvt_pk_bf16_f32 v58, v67, v61
	v_cvt_pk_bf16_f32 v59, v62, v59
	v_pk_mul_f32 v[54:55], v[54:55], v[66:67] op_sel_hi:[1,0]
	v_pk_mul_f32 v[52:53], v[52:53], v[66:67] op_sel_hi:[1,0]
	v_max_f32_e32 v48, 0, v48
	v_max_f32_e32 v49, 0, v49
	v_max_f32_e32 v50, 0, v50
	global_store_dwordx4 v[64:65], v[56:59], off
	v_max_f32_e32 v52, 0, v52
	v_max_f32_e32 v51, 0, v51
	v_mul_f32_e32 v56, v48, v48
	v_max_f32_e32 v48, 0, v53
	v_mul_f32_e32 v53, v49, v49
	v_max_f32_e32 v49, 0, v54
	v_mul_f32_e32 v54, v50, v50
	v_max_f32_e32 v50, 0, v55
	v_mul_f32_e32 v52, v52, v52
	v_mul_f32_e32 v48, v48, v48
	v_mul_f32_e32 v49, v49, v49
	v_mul_f32_e32 v50, v50, v50
	v_mul_f32_e32 v51, v51, v51
	v_cvt_pk_bf16_f32 v48, v52, v48
	v_cvt_pk_bf16_f32 v49, v49, v50
	v_cvt_pk_bf16_f32 v50, v56, v53
	v_cvt_pk_bf16_f32 v51, v54, v51
	global_store_dwordx4 v[64:65], v[48:51], off offset:256
	v_mov_b32_e32 v52, 0
	s_nop 0
	v_add_u32_e32 v48, 0x90, v148
	v_ashrrev_i32_e32 v49, 31, v48
	v_lshlrev_b64 v[50:51], 7, v[48:49]
	v_lshl_add_u64 v[50:51], s[52:53], 0, v[50:51]
	v_lshl_add_u64 v[50:51], v[136:137], 4, v[50:51]
	v_lshlrev_b64 v[48:49], 14, v[48:49]
	v_lshl_add_u64 v[48:49], s[50:51], 0, v[48:49]
	v_lshl_add_u64 v[48:49], v[146:147], 1, v[48:49]
	s_waitcnt lgkmcnt(0)
	s_waitcnt lgkmcnt(0)
	v_mov_b32_e32 v50, v206
	s_nop 0
	v_pk_mul_f32 v[44:45], v[44:45], v[50:51] op_sel_hi:[1,0]
	v_pk_mul_f32 v[42:43], v[42:43], v[50:51] op_sel_hi:[1,0]
	v_pk_mul_f32 v[40:41], v[40:41], v[50:51] op_sel_hi:[1,0]
	v_pk_mul_f32 v[46:47], v[46:47], v[50:51] op_sel_hi:[1,0]
	v_max_f32_e32 v40, 0, v40
	v_max_f32_e32 v45, 0, v45
	v_max_f32_e32 v41, 0, v41
	v_max_f32_e32 v42, 0, v42
	v_max_f32_e32 v44, 0, v44
	v_mul_f32_e32 v51, v40, v40
	v_mul_f32_e32 v40, v45, v45
	v_mul_f32_e32 v45, v41, v41
	v_max_f32_e32 v41, 0, v46
	v_mul_f32_e32 v46, v42, v42
	v_max_f32_e32 v42, 0, v47
	v_max_f32_e32 v43, 0, v43
	v_mul_f32_e32 v44, v44, v44
	v_mul_f32_e32 v41, v41, v41
	v_mul_f32_e32 v42, v42, v42
	v_mul_f32_e32 v43, v43, v43
	v_pk_mul_f32 v[34:35], v[34:35], v[50:51] op_sel_hi:[1,0]
	v_pk_mul_f32 v[32:33], v[32:33], v[50:51] op_sel_hi:[1,0]
	v_cvt_pk_bf16_f32 v40, v44, v40
	v_cvt_pk_bf16_f32 v41, v41, v42
	v_cvt_pk_bf16_f32 v42, v51, v45
	v_cvt_pk_bf16_f32 v43, v46, v43
	v_pk_mul_f32 v[38:39], v[38:39], v[50:51] op_sel_hi:[1,0]
	v_pk_mul_f32 v[36:37], v[36:37], v[50:51] op_sel_hi:[1,0]
	v_max_f32_e32 v32, 0, v32
	v_max_f32_e32 v33, 0, v33
	v_max_f32_e32 v34, 0, v34
	global_store_dwordx4 v[48:49], v[40:43], off
	v_max_f32_e32 v36, 0, v36
	v_max_f32_e32 v35, 0, v35
	v_mul_f32_e32 v40, v32, v32
	v_max_f32_e32 v32, 0, v37
	v_mul_f32_e32 v37, v33, v33
	v_max_f32_e32 v33, 0, v38
	v_mul_f32_e32 v38, v34, v34
	v_max_f32_e32 v34, 0, v39
	v_mul_f32_e32 v36, v36, v36
	v_mul_f32_e32 v32, v32, v32
	v_mul_f32_e32 v33, v33, v33
	v_mul_f32_e32 v34, v34, v34
	v_mul_f32_e32 v35, v35, v35
	v_cvt_pk_bf16_f32 v32, v36, v32
	v_cvt_pk_bf16_f32 v33, v33, v34
	v_cvt_pk_bf16_f32 v34, v40, v37
	v_cvt_pk_bf16_f32 v35, v38, v35
	global_store_dwordx4 v[48:49], v[32:35], off offset:256
	v_mov_b32_e32 v36, 0
	s_nop 0
	v_add_u32_e32 v32, 0xa0, v148
	v_ashrrev_i32_e32 v33, 31, v32
	v_lshlrev_b64 v[34:35], 7, v[32:33]
	v_lshl_add_u64 v[34:35], s[52:53], 0, v[34:35]
	v_lshl_add_u64 v[34:35], v[136:137], 4, v[34:35]
	v_lshlrev_b64 v[32:33], 14, v[32:33]
	v_lshl_add_u64 v[32:33], s[50:51], 0, v[32:33]
	v_lshl_add_u64 v[32:33], v[146:147], 1, v[32:33]
	s_waitcnt lgkmcnt(0)
	s_waitcnt lgkmcnt(0)
	v_mov_b32_e32 v34, v214
	s_nop 0
	v_pk_mul_f32 v[28:29], v[28:29], v[34:35] op_sel_hi:[1,0]
	v_pk_mul_f32 v[26:27], v[26:27], v[34:35] op_sel_hi:[1,0]
	v_pk_mul_f32 v[24:25], v[24:25], v[34:35] op_sel_hi:[1,0]
	v_pk_mul_f32 v[30:31], v[30:31], v[34:35] op_sel_hi:[1,0]
	v_max_f32_e32 v24, 0, v24
	v_max_f32_e32 v29, 0, v29
	v_max_f32_e32 v25, 0, v25
	v_max_f32_e32 v26, 0, v26
	v_max_f32_e32 v28, 0, v28
	v_mul_f32_e32 v35, v24, v24
	v_mul_f32_e32 v24, v29, v29
	v_mul_f32_e32 v29, v25, v25
	v_max_f32_e32 v25, 0, v30
	v_mul_f32_e32 v30, v26, v26
	v_max_f32_e32 v26, 0, v31
	v_max_f32_e32 v27, 0, v27
	v_mul_f32_e32 v28, v28, v28
	v_mul_f32_e32 v25, v25, v25
	v_mul_f32_e32 v26, v26, v26
	v_mul_f32_e32 v27, v27, v27
	v_pk_mul_f32 v[18:19], v[18:19], v[34:35] op_sel_hi:[1,0]
	v_pk_mul_f32 v[16:17], v[16:17], v[34:35] op_sel_hi:[1,0]
	v_cvt_pk_bf16_f32 v24, v28, v24
	v_cvt_pk_bf16_f32 v25, v25, v26
	v_cvt_pk_bf16_f32 v26, v35, v29
	v_cvt_pk_bf16_f32 v27, v30, v27
	v_pk_mul_f32 v[22:23], v[22:23], v[34:35] op_sel_hi:[1,0]
	v_pk_mul_f32 v[20:21], v[20:21], v[34:35] op_sel_hi:[1,0]
	v_max_f32_e32 v16, 0, v16
	v_max_f32_e32 v17, 0, v17
	v_max_f32_e32 v18, 0, v18
	global_store_dwordx4 v[32:33], v[24:27], off
	v_max_f32_e32 v20, 0, v20
	v_max_f32_e32 v19, 0, v19
	v_mul_f32_e32 v24, v16, v16
	v_max_f32_e32 v16, 0, v21
	v_mul_f32_e32 v21, v17, v17
	v_max_f32_e32 v17, 0, v22
	v_mul_f32_e32 v22, v18, v18
	v_max_f32_e32 v18, 0, v23
	v_mul_f32_e32 v20, v20, v20
	v_mul_f32_e32 v16, v16, v16
	v_mul_f32_e32 v17, v17, v17
	v_mul_f32_e32 v18, v18, v18
	v_mul_f32_e32 v19, v19, v19
	v_cvt_pk_bf16_f32 v16, v20, v16
	v_cvt_pk_bf16_f32 v17, v17, v18
	v_cvt_pk_bf16_f32 v18, v24, v21
	v_cvt_pk_bf16_f32 v19, v22, v19
	global_store_dwordx4 v[32:33], v[16:19], off offset:256
	v_mov_b32_e32 v20, 0
	s_nop 0
	v_add_u32_e32 v16, 0xb0, v148
	v_ashrrev_i32_e32 v17, 31, v16
	v_lshlrev_b64 v[18:19], 7, v[16:17]
	v_lshl_add_u64 v[18:19], s[52:53], 0, v[18:19]
	v_lshl_add_u64 v[18:19], v[136:137], 4, v[18:19]
	v_lshlrev_b64 v[16:17], 14, v[16:17]
	v_lshl_add_u64 v[16:17], s[50:51], 0, v[16:17]
	v_lshl_add_u64 v[16:17], v[146:147], 1, v[16:17]
	s_andn2_b64 vcc, exec, s[18:19]
	s_waitcnt lgkmcnt(0)
	s_mov_b64 s[18:19], -1
	s_waitcnt lgkmcnt(0)
	v_mov_b32_e32 v18, v222
	s_nop 0
	v_pk_mul_f32 v[12:13], v[12:13], v[18:19] op_sel_hi:[1,0]
	v_pk_mul_f32 v[10:11], v[10:11], v[18:19] op_sel_hi:[1,0]
	v_pk_mul_f32 v[8:9], v[8:9], v[18:19] op_sel_hi:[1,0]
	v_pk_mul_f32 v[14:15], v[14:15], v[18:19] op_sel_hi:[1,0]
	v_max_f32_e32 v8, 0, v8
	v_max_f32_e32 v13, 0, v13
	v_max_f32_e32 v9, 0, v9
	v_max_f32_e32 v10, 0, v10
	v_max_f32_e32 v12, 0, v12
	v_mul_f32_e32 v19, v8, v8
	v_mul_f32_e32 v8, v13, v13
	v_mul_f32_e32 v13, v9, v9
	v_max_f32_e32 v9, 0, v14
	v_mul_f32_e32 v14, v10, v10
	v_max_f32_e32 v10, 0, v15
	v_max_f32_e32 v11, 0, v11
	v_mul_f32_e32 v12, v12, v12
	v_mul_f32_e32 v9, v9, v9
	v_mul_f32_e32 v10, v10, v10
	v_mul_f32_e32 v11, v11, v11
	v_pk_mul_f32 v[2:3], v[2:3], v[18:19] op_sel_hi:[1,0]
	v_pk_mul_f32 v[0:1], v[0:1], v[18:19] op_sel_hi:[1,0]
	v_cvt_pk_bf16_f32 v8, v12, v8
	v_cvt_pk_bf16_f32 v9, v9, v10
	v_cvt_pk_bf16_f32 v10, v19, v13
	v_cvt_pk_bf16_f32 v11, v14, v11
	v_pk_mul_f32 v[6:7], v[6:7], v[18:19] op_sel_hi:[1,0]
	v_pk_mul_f32 v[4:5], v[4:5], v[18:19] op_sel_hi:[1,0]
	v_max_f32_e32 v0, 0, v0
	v_max_f32_e32 v1, 0, v1
	v_max_f32_e32 v2, 0, v2
	global_store_dwordx4 v[16:17], v[8:11], off
	v_max_f32_e32 v4, 0, v4
	v_max_f32_e32 v3, 0, v3
	v_mul_f32_e32 v8, v0, v0
	v_max_f32_e32 v0, 0, v5
	v_mul_f32_e32 v5, v1, v1
	v_max_f32_e32 v1, 0, v6
	v_mul_f32_e32 v6, v2, v2
	v_max_f32_e32 v2, 0, v7
	v_mul_f32_e32 v4, v4, v4
	v_mul_f32_e32 v0, v0, v0
	v_mul_f32_e32 v1, v1, v1
	v_mul_f32_e32 v2, v2, v2
	v_mul_f32_e32 v3, v3, v3
	v_cvt_pk_bf16_f32 v0, v4, v0
	v_cvt_pk_bf16_f32 v1, v1, v2
	v_cvt_pk_bf16_f32 v2, v8, v5
	v_cvt_pk_bf16_f32 v3, v6, v3
	global_store_dwordx4 v[16:17], v[0:3], off offset:256
	s_cbranch_vccnz .LBB0_1777
	s_and_b64 vcc, exec, s[10:11]
	s_cbranch_vccnz .LBB0_1776
	s_barrier
	s_branch .LBB0_1776

.LBB0_2538:
	v_lshl_add_u32 v146, s76, 8, v150
	v_ashrrev_i32_e32 v147, 31, v146
	v_mov_b32_e32 v199, 0
	v_mov_b32_e32 v198, v146
	v_lshlrev_b64 v[200:201], 7, v[198:199]
	v_lshl_add_u64 v[200:201], v[136:137], 0, v[200:201]
	global_load_dwordx4 v[166:169], v[200:201], off offset:48
	v_add_u32_e32 v198, 16, v146
	v_lshlrev_b64 v[200:201], 7, v[198:199]
	v_lshl_add_u64 v[200:201], v[136:137], 0, v[200:201]
	global_load_dwordx4 v[170:173], v[200:201], off offset:48
	v_add_u32_e32 v198, 32, v146
	v_lshlrev_b64 v[200:201], 7, v[198:199]
	v_lshl_add_u64 v[200:201], v[136:137], 0, v[200:201]
	global_load_dwordx4 v[174:177], v[200:201], off offset:48
	v_add_u32_e32 v198, 48, v146
	v_lshlrev_b64 v[200:201], 7, v[198:199]
	v_lshl_add_u64 v[200:201], v[136:137], 0, v[200:201]
	global_load_dwordx4 v[178:181], v[200:201], off offset:48
	v_add_u32_e32 v198, 128, v146
	v_lshlrev_b64 v[200:201], 7, v[198:199]
	v_lshl_add_u64 v[200:201], v[136:137], 0, v[200:201]
	global_load_dwordx4 v[182:185], v[200:201], off offset:48
	v_add_u32_e32 v198, 144, v146
	v_lshlrev_b64 v[200:201], 7, v[198:199]
	v_lshl_add_u64 v[200:201], v[136:137], 0, v[200:201]
	global_load_dwordx4 v[186:189], v[200:201], off offset:48
	v_add_u32_e32 v198, 160, v146
	v_lshlrev_b64 v[200:201], 7, v[198:199]
	v_lshl_add_u64 v[200:201], v[136:137], 0, v[200:201]
	global_load_dwordx4 v[190:193], v[200:201], off offset:48
	v_add_u32_e32 v198, 176, v146
	v_lshlrev_b64 v[200:201], 7, v[198:199]
	v_lshl_add_u64 v[200:201], v[136:137], 0, v[200:201]
	global_load_dwordx4 v[194:197], v[200:201], off offset:48
	s_waitcnt vmcnt(0)
	v_add_f32_e32 v166, v167, v166
	v_add_f32_e32 v168, v168, v169
	v_add_f32_e32 v166, v166, v168
	v_cndmask_b32_e64 v166, 0, v166, s[6:7]
	v_add_f32_e32 v170, v171, v170
	v_add_f32_e32 v172, v172, v173
	v_add_f32_e32 v170, v170, v172
	v_cndmask_b32_e64 v170, 0, v170, s[6:7]
	v_add_f32_e32 v174, v175, v174
	v_add_f32_e32 v176, v176, v177
	v_add_f32_e32 v174, v174, v176
	v_cndmask_b32_e64 v174, 0, v174, s[6:7]
	v_add_f32_e32 v178, v179, v178
	v_add_f32_e32 v180, v180, v181
	v_add_f32_e32 v178, v178, v180
	v_cndmask_b32_e64 v178, 0, v178, s[6:7]
	v_add_f32_e32 v182, v183, v182
	v_add_f32_e32 v184, v184, v185
	v_add_f32_e32 v182, v182, v184
	v_cndmask_b32_e64 v182, 0, v182, s[6:7]
	v_add_f32_e32 v186, v187, v186
	v_add_f32_e32 v188, v188, v189
	v_add_f32_e32 v186, v186, v188
	v_cndmask_b32_e64 v186, 0, v186, s[6:7]
	v_add_f32_e32 v190, v191, v190
	v_add_f32_e32 v192, v192, v193
	v_add_f32_e32 v190, v190, v192
	v_cndmask_b32_e64 v190, 0, v190, s[6:7]
	v_add_f32_e32 v194, v195, v194
	v_add_f32_e32 v196, v196, v197
	v_add_f32_e32 v194, v194, v196
	v_cndmask_b32_e64 v194, 0, v194, s[6:7]
	ds_bpermute_b32 v167, v153, v166
	ds_bpermute_b32 v171, v153, v170
	ds_bpermute_b32 v175, v153, v174
	ds_bpermute_b32 v179, v153, v178
	ds_bpermute_b32 v183, v153, v182
	ds_bpermute_b32 v187, v153, v186
	ds_bpermute_b32 v191, v153, v190
	ds_bpermute_b32 v195, v153, v194
	s_waitcnt lgkmcnt(0)
	v_add_f32_e32 v166, v166, v167
	v_add_f32_e32 v170, v170, v171
	v_add_f32_e32 v174, v174, v175
	v_add_f32_e32 v178, v178, v179
	v_add_f32_e32 v182, v182, v183
	v_add_f32_e32 v186, v186, v187
	v_add_f32_e32 v190, v190, v191
	v_add_f32_e32 v194, v194, v195
	ds_bpermute_b32 v167, v154, v166
	ds_bpermute_b32 v171, v154, v170
	ds_bpermute_b32 v175, v154, v174
	ds_bpermute_b32 v179, v154, v178
	ds_bpermute_b32 v183, v154, v182
	ds_bpermute_b32 v187, v154, v186
	ds_bpermute_b32 v191, v154, v190
	ds_bpermute_b32 v195, v154, v194
	s_waitcnt lgkmcnt(0)
	v_add_f32_e32 v166, v166, v167
	v_add_f32_e32 v170, v170, v171
	v_add_f32_e32 v174, v174, v175
	v_add_f32_e32 v178, v178, v179
	v_add_f32_e32 v182, v182, v183
	v_add_f32_e32 v186, v186, v187
	v_add_f32_e32 v190, v190, v191
	v_add_f32_e32 v194, v194, v195
	v_fmamk_f32 v166, v166, 0x3b000000, v158
	v_fmamk_f32 v170, v170, 0x3b000000, v158
	v_fmamk_f32 v174, v174, 0x3b000000, v158
	v_fmamk_f32 v178, v178, 0x3b000000, v158
	v_fmamk_f32 v182, v182, 0x3b000000, v158
	v_fmamk_f32 v186, v186, 0x3b000000, v158
	v_fmamk_f32 v190, v190, 0x3b000000, v158
	v_fmamk_f32 v194, v194, 0x3b000000, v158
	v_rsq_f32_e32 v166, v166
	v_rsq_f32_e32 v170, v170
	v_rsq_f32_e32 v174, v174
	v_rsq_f32_e32 v178, v178
	v_rsq_f32_e32 v182, v182
	v_rsq_f32_e32 v186, v186
	v_rsq_f32_e32 v190, v190
	v_rsq_f32_e32 v194, v194
	s_nop 0
	v_mov_b32_e32 v159, 0
	v_mov_b32_e32 v148, 0
	v_lshlrev_b64 v[160:161], 13, v[146:147]
	v_lshl_add_u64 v[160:161], s[20:21], 0, v[160:161]
	s_waitcnt lgkmcnt(0)
	v_lshl_add_u32 v148, s66, 8, v152
	s_waitcnt lgkmcnt(0)
	v_mov_b32_e32 v162, v166
	v_ashrrev_i32_e32 v149, 31, v148
	v_lshl_add_u64 v[160:161], v[148:149], 1, v[160:161]
	v_pk_mul_f32 v[126:127], v[126:127], v[162:163] op_sel_hi:[1,0]
	v_pk_mul_f32 v[124:125], v[124:125], v[162:163] op_sel_hi:[1,0]
	v_pk_mul_f32 v[164:165], v[122:123], v[162:163] op_sel_hi:[1,0]
	v_pk_mul_f32 v[122:123], v[120:121], v[162:163] op_sel_hi:[1,0]
	v_cvt_pk_bf16_f32 v120, v124, v125
	v_cvt_pk_bf16_f32 v121, v126, v127
	v_cvt_pk_bf16_f32 v122, v122, v123
	v_cvt_pk_bf16_f32 v123, v164, v165
	global_store_dwordx4 v[160:161], v[120:123], off
	v_pk_mul_f32 v[118:119], v[118:119], v[162:163] op_sel_hi:[1,0]
	v_pk_mul_f32 v[116:117], v[116:117], v[162:163] op_sel_hi:[1,0]
	v_pk_mul_f32 v[120:121], v[114:115], v[162:163] op_sel_hi:[1,0]
	v_pk_mul_f32 v[114:115], v[112:113], v[162:163] op_sel_hi:[1,0]
	v_cvt_pk_bf16_f32 v112, v116, v117
	v_cvt_pk_bf16_f32 v113, v118, v119
	v_cvt_pk_bf16_f32 v114, v114, v115
	v_cvt_pk_bf16_f32 v115, v120, v121
	global_store_dwordx4 v[160:161], v[112:115], off offset:256
	s_nop 1
	v_or_b32_e32 v112, 16, v146
	v_ashrrev_i32_e32 v113, 31, v112
	v_lshlrev_b64 v[112:113], 13, v[112:113]
	v_lshl_add_u64 v[112:113], s[20:21], 0, v[112:113]
	v_lshl_add_u64 v[112:113], v[148:149], 1, v[112:113]
	s_waitcnt lgkmcnt(0)
	s_waitcnt lgkmcnt(0)
	v_mov_b32_e32 v114, v170
	s_nop 0
	v_pk_mul_f32 v[110:111], v[110:111], v[114:115] op_sel_hi:[1,0]
	v_pk_mul_f32 v[108:109], v[108:109], v[114:115] op_sel_hi:[1,0]
	v_pk_mul_f32 v[106:107], v[106:107], v[114:115] op_sel_hi:[1,0]
	v_pk_mul_f32 v[104:105], v[104:105], v[114:115] op_sel_hi:[1,0]
	v_pk_mul_f32 v[116:117], v[102:103], v[114:115] op_sel_hi:[1,0]
	v_pk_mul_f32 v[118:119], v[100:101], v[114:115] op_sel_hi:[1,0]
	v_cvt_pk_bf16_f32 v100, v108, v109
	v_cvt_pk_bf16_f32 v101, v110, v111
	v_cvt_pk_bf16_f32 v102, v104, v105
	v_cvt_pk_bf16_f32 v103, v106, v107
	global_store_dwordx4 v[112:113], v[100:103], off
	s_nop 1
	v_pk_mul_f32 v[100:101], v[98:99], v[114:115] op_sel_hi:[1,0]
	v_pk_mul_f32 v[98:99], v[96:97], v[114:115] op_sel_hi:[1,0]
	v_cvt_pk_bf16_f32 v96, v118, v119
	v_cvt_pk_bf16_f32 v97, v116, v117
	v_cvt_pk_bf16_f32 v98, v98, v99
	v_cvt_pk_bf16_f32 v99, v100, v101
	global_store_dwordx4 v[112:113], v[96:99], off offset:256
	s_nop 1
	v_or_b32_e32 v96, 32, v146
	v_ashrrev_i32_e32 v97, 31, v96
	v_mov_b32_e32 v98, 0
	v_mov_b32_e32 v99, 0
	v_lshlrev_b64 v[96:97], 13, v[96:97]
	v_lshl_add_u64 v[96:97], s[20:21], 0, v[96:97]
	v_lshl_add_u64 v[96:97], v[148:149], 1, v[96:97]
	s_waitcnt lgkmcnt(0)
	s_waitcnt lgkmcnt(0)
	v_mov_b32_e32 v100, v174
	s_nop 0
	v_pk_mul_f32 v[94:95], v[94:95], v[100:101] op_sel_hi:[1,0]
	v_pk_mul_f32 v[92:93], v[92:93], v[100:101] op_sel_hi:[1,0]
	v_pk_mul_f32 v[90:91], v[90:91], v[100:101] op_sel_hi:[1,0]
	v_pk_mul_f32 v[88:89], v[88:89], v[100:101] op_sel_hi:[1,0]
	v_pk_mul_f32 v[102:103], v[86:87], v[100:101] op_sel_hi:[1,0]
	v_pk_mul_f32 v[104:105], v[84:85], v[100:101] op_sel_hi:[1,0]
	v_cvt_pk_bf16_f32 v84, v92, v93
	v_cvt_pk_bf16_f32 v85, v94, v95
	v_cvt_pk_bf16_f32 v86, v88, v89
	v_cvt_pk_bf16_f32 v87, v90, v91
	global_store_dwordx4 v[96:97], v[84:87], off
	s_nop 1
	v_pk_mul_f32 v[84:85], v[82:83], v[100:101] op_sel_hi:[1,0]
	v_pk_mul_f32 v[82:83], v[80:81], v[100:101] op_sel_hi:[1,0]
	v_cvt_pk_bf16_f32 v80, v104, v105
	v_cvt_pk_bf16_f32 v81, v102, v103
	v_cvt_pk_bf16_f32 v82, v82, v83
	v_cvt_pk_bf16_f32 v83, v84, v85
	global_store_dwordx4 v[96:97], v[80:83], off offset:256
	s_nop 1
	v_or_b32_e32 v80, 48, v146
	v_ashrrev_i32_e32 v81, 31, v80
	v_lshlrev_b64 v[80:81], 13, v[80:81]
	v_lshl_add_u64 v[80:81], s[20:21], 0, v[80:81]
	v_lshl_add_u64 v[80:81], v[148:149], 1, v[80:81]
	s_waitcnt lgkmcnt(0)
	s_waitcnt lgkmcnt(0)
	v_mov_b32_e32 v82, v178
	s_nop 0
	v_pk_mul_f32 v[78:79], v[78:79], v[82:83] op_sel_hi:[1,0]
	v_pk_mul_f32 v[76:77], v[76:77], v[82:83] op_sel_hi:[1,0]
	v_pk_mul_f32 v[74:75], v[74:75], v[82:83] op_sel_hi:[1,0]
	v_pk_mul_f32 v[72:73], v[72:73], v[82:83] op_sel_hi:[1,0]
	v_pk_mul_f32 v[84:85], v[70:71], v[82:83] op_sel_hi:[1,0]
	v_pk_mul_f32 v[86:87], v[68:69], v[82:83] op_sel_hi:[1,0]
	v_cvt_pk_bf16_f32 v68, v76, v77
	v_cvt_pk_bf16_f32 v69, v78, v79
	v_cvt_pk_bf16_f32 v70, v72, v73
	v_cvt_pk_bf16_f32 v71, v74, v75
	global_store_dwordx4 v[80:81], v[68:71], off
	s_nop 1
	v_pk_mul_f32 v[68:69], v[66:67], v[82:83] op_sel_hi:[1,0]
	v_pk_mul_f32 v[66:67], v[64:65], v[82:83] op_sel_hi:[1,0]
	v_cvt_pk_bf16_f32 v64, v86, v87
	v_cvt_pk_bf16_f32 v65, v84, v85
	v_cvt_pk_bf16_f32 v66, v66, v67
	v_cvt_pk_bf16_f32 v67, v68, v69
	global_store_dwordx4 v[80:81], v[64:67], off offset:256
	s_nop 1
	v_add_u32_e32 v64, 0x80, v146
	v_ashrrev_i32_e32 v65, 31, v64
	v_mov_b32_e32 v66, 0
	v_mov_b32_e32 v67, 0
	v_lshlrev_b64 v[64:65], 13, v[64:65]
	v_lshl_add_u64 v[64:65], s[20:21], 0, v[64:65]
	v_lshl_add_u64 v[64:65], v[148:149], 1, v[64:65]
	s_waitcnt lgkmcnt(0)
	s_waitcnt lgkmcnt(0)
	v_mov_b32_e32 v68, v182
	s_nop 0
	v_pk_mul_f32 v[62:63], v[62:63], v[68:69] op_sel_hi:[1,0]
	v_pk_mul_f32 v[60:61], v[60:61], v[68:69] op_sel_hi:[1,0]
	v_pk_mul_f32 v[58:59], v[58:59], v[68:69] op_sel_hi:[1,0]
	v_pk_mul_f32 v[56:57], v[56:57], v[68:69] op_sel_hi:[1,0]
	v_pk_mul_f32 v[70:71], v[54:55], v[68:69] op_sel_hi:[1,0]
	v_pk_mul_f32 v[72:73], v[52:53], v[68:69] op_sel_hi:[1,0]
	v_cvt_pk_bf16_f32 v52, v60, v61
	v_cvt_pk_bf16_f32 v53, v62, v63
	v_cvt_pk_bf16_f32 v54, v56, v57
	v_cvt_pk_bf16_f32 v55, v58, v59
	global_store_dwordx4 v[64:65], v[52:55], off
	s_nop 1
	v_pk_mul_f32 v[52:53], v[50:51], v[68:69] op_sel_hi:[1,0]
	v_pk_mul_f32 v[50:51], v[48:49], v[68:69] op_sel_hi:[1,0]
	v_cvt_pk_bf16_f32 v48, v72, v73
	v_cvt_pk_bf16_f32 v49, v70, v71
	v_cvt_pk_bf16_f32 v50, v50, v51
	v_cvt_pk_bf16_f32 v51, v52, v53
	global_store_dwordx4 v[64:65], v[48:51], off offset:256
	s_nop 1
	v_add_u32_e32 v48, 0x90, v146
	v_ashrrev_i32_e32 v49, 31, v48
	v_lshlrev_b64 v[48:49], 13, v[48:49]
	v_lshl_add_u64 v[48:49], s[20:21], 0, v[48:49]
	v_lshl_add_u64 v[48:49], v[148:149], 1, v[48:49]
	s_waitcnt lgkmcnt(0)
	s_waitcnt lgkmcnt(0)
	v_mov_b32_e32 v50, v186
	s_nop 0
	v_pk_mul_f32 v[46:47], v[46:47], v[50:51] op_sel_hi:[1,0]
	v_pk_mul_f32 v[44:45], v[44:45], v[50:51] op_sel_hi:[1,0]
	v_pk_mul_f32 v[42:43], v[42:43], v[50:51] op_sel_hi:[1,0]
	v_pk_mul_f32 v[40:41], v[40:41], v[50:51] op_sel_hi:[1,0]
	v_pk_mul_f32 v[52:53], v[38:39], v[50:51] op_sel_hi:[1,0]
	v_pk_mul_f32 v[54:55], v[36:37], v[50:51] op_sel_hi:[1,0]
	v_cvt_pk_bf16_f32 v36, v44, v45
	v_cvt_pk_bf16_f32 v37, v46, v47
	v_cvt_pk_bf16_f32 v38, v40, v41
	v_cvt_pk_bf16_f32 v39, v42, v43
	global_store_dwordx4 v[48:49], v[36:39], off
	s_nop 1
	v_pk_mul_f32 v[36:37], v[34:35], v[50:51] op_sel_hi:[1,0]
	v_pk_mul_f32 v[34:35], v[32:33], v[50:51] op_sel_hi:[1,0]
	v_cvt_pk_bf16_f32 v32, v54, v55
	v_cvt_pk_bf16_f32 v33, v52, v53
	v_cvt_pk_bf16_f32 v34, v34, v35
	v_cvt_pk_bf16_f32 v35, v36, v37
	global_store_dwordx4 v[48:49], v[32:35], off offset:256
	s_nop 1
	v_add_u32_e32 v32, 0xa0, v146
	v_ashrrev_i32_e32 v33, 31, v32
	v_mov_b32_e32 v34, 0
	v_mov_b32_e32 v35, 0
	v_lshlrev_b64 v[32:33], 13, v[32:33]
	v_lshl_add_u64 v[32:33], s[20:21], 0, v[32:33]
	v_lshl_add_u64 v[32:33], v[148:149], 1, v[32:33]
	s_waitcnt lgkmcnt(0)
	s_waitcnt lgkmcnt(0)
	v_mov_b32_e32 v36, v190
	s_nop 0
	v_pk_mul_f32 v[30:31], v[30:31], v[36:37] op_sel_hi:[1,0]
	v_pk_mul_f32 v[28:29], v[28:29], v[36:37] op_sel_hi:[1,0]
	v_pk_mul_f32 v[26:27], v[26:27], v[36:37] op_sel_hi:[1,0]
	v_pk_mul_f32 v[24:25], v[24:25], v[36:37] op_sel_hi:[1,0]
	v_pk_mul_f32 v[38:39], v[22:23], v[36:37] op_sel_hi:[1,0]
	v_pk_mul_f32 v[40:41], v[20:21], v[36:37] op_sel_hi:[1,0]
	v_cvt_pk_bf16_f32 v20, v28, v29
	v_cvt_pk_bf16_f32 v21, v30, v31
	v_cvt_pk_bf16_f32 v22, v24, v25
	v_cvt_pk_bf16_f32 v23, v26, v27
	global_store_dwordx4 v[32:33], v[20:23], off
	s_nop 1
	v_pk_mul_f32 v[20:21], v[18:19], v[36:37] op_sel_hi:[1,0]
	v_pk_mul_f32 v[18:19], v[16:17], v[36:37] op_sel_hi:[1,0]
	v_cvt_pk_bf16_f32 v16, v40, v41
	v_cvt_pk_bf16_f32 v17, v38, v39
	v_cvt_pk_bf16_f32 v18, v18, v19
	v_cvt_pk_bf16_f32 v19, v20, v21
	global_store_dwordx4 v[32:33], v[16:19], off offset:256
	s_nop 1
	v_add_u32_e32 v16, 0xb0, v146
	v_ashrrev_i32_e32 v17, 31, v16
	v_lshlrev_b64 v[16:17], 13, v[16:17]
	v_lshl_add_u64 v[16:17], s[20:21], 0, v[16:17]
	v_lshl_add_u64 v[16:17], v[148:149], 1, v[16:17]
	s_and_b64 vcc, exec, s[14:15]
	s_waitcnt lgkmcnt(0)
	s_mov_b64 s[14:15], -1
	s_waitcnt lgkmcnt(0)
	v_mov_b32_e32 v18, v194
	s_nop 0
	v_pk_mul_f32 v[14:15], v[14:15], v[18:19] op_sel_hi:[1,0]
	v_pk_mul_f32 v[12:13], v[12:13], v[18:19] op_sel_hi:[1,0]
	v_pk_mul_f32 v[10:11], v[10:11], v[18:19] op_sel_hi:[1,0]
	v_pk_mul_f32 v[8:9], v[8:9], v[18:19] op_sel_hi:[1,0]
	v_pk_mul_f32 v[20:21], v[6:7], v[18:19] op_sel_hi:[1,0]
	v_pk_mul_f32 v[22:23], v[4:5], v[18:19] op_sel_hi:[1,0]
	v_cvt_pk_bf16_f32 v4, v12, v13
	v_cvt_pk_bf16_f32 v5, v14, v15
	v_cvt_pk_bf16_f32 v6, v8, v9
	v_cvt_pk_bf16_f32 v7, v10, v11
	global_store_dwordx4 v[16:17], v[4:7], off
	s_nop 1
	v_pk_mul_f32 v[4:5], v[2:3], v[18:19] op_sel_hi:[1,0]
	v_pk_mul_f32 v[2:3], v[0:1], v[18:19] op_sel_hi:[1,0]
	v_cvt_pk_bf16_f32 v0, v22, v23
	v_cvt_pk_bf16_f32 v1, v20, v21
	v_cvt_pk_bf16_f32 v2, v2, v3
	v_cvt_pk_bf16_f32 v3, v4, v5
	global_store_dwordx4 v[16:17], v[0:3], off offset:256
	s_cbranch_vccnz .LBB0_2525
	s_and_b64 vcc, exec, s[10:11]
	s_cbranch_vccnz .LBB0_2524
	s_barrier
	s_branch .LBB0_2524

.LBB0_2808:
	v_lshl_add_u32 v148, s44, 8, v150
	v_ashrrev_i32_e32 v149, 31, v148
	v_mov_b32_e32 v227, 0
	v_mov_b32_e32 v226, v148
	v_lshlrev_b64 v[228:229], 7, v[226:227]
	v_lshl_add_u64 v[228:229], s[52:53], 0, v[228:229]
	v_lshl_add_u64 v[228:229], v[136:137], 4, v[228:229]
	global_load_dwordx4 v[166:169], v[228:229], off
	global_load_dwordx4 v[170:173], v[228:229], off offset:64
	v_add_u32_e32 v226, 16, v148
	v_lshlrev_b64 v[228:229], 7, v[226:227]
	v_lshl_add_u64 v[228:229], s[52:53], 0, v[228:229]
	v_lshl_add_u64 v[228:229], v[136:137], 4, v[228:229]
	global_load_dwordx4 v[174:177], v[228:229], off
	global_load_dwordx4 v[178:181], v[228:229], off offset:64
	v_add_u32_e32 v226, 32, v148
	v_lshlrev_b64 v[228:229], 7, v[226:227]
	v_lshl_add_u64 v[228:229], s[52:53], 0, v[228:229]
	v_lshl_add_u64 v[228:229], v[136:137], 4, v[228:229]
	global_load_dwordx4 v[182:185], v[228:229], off
	global_load_dwordx4 v[186:189], v[228:229], off offset:64
	v_add_u32_e32 v226, 48, v148
	v_lshlrev_b64 v[228:229], 7, v[226:227]
	v_lshl_add_u64 v[228:229], s[52:53], 0, v[228:229]
	v_lshl_add_u64 v[228:229], v[136:137], 4, v[228:229]
	global_load_dwordx4 v[190:193], v[228:229], off
	global_load_dwordx4 v[194:197], v[228:229], off offset:64
	v_add_u32_e32 v226, 128, v148
	v_lshlrev_b64 v[228:229], 7, v[226:227]
	v_lshl_add_u64 v[228:229], s[52:53], 0, v[228:229]
	v_lshl_add_u64 v[228:229], v[136:137], 4, v[228:229]
	global_load_dwordx4 v[198:201], v[228:229], off
	global_load_dwordx4 v[202:205], v[228:229], off offset:64
	v_add_u32_e32 v226, 144, v148
	v_lshlrev_b64 v[228:229], 7, v[226:227]
	v_lshl_add_u64 v[228:229], s[52:53], 0, v[228:229]
	v_lshl_add_u64 v[228:229], v[136:137], 4, v[228:229]
	global_load_dwordx4 v[206:209], v[228:229], off
	global_load_dwordx4 v[210:213], v[228:229], off offset:64
	v_add_u32_e32 v226, 160, v148
	v_lshlrev_b64 v[228:229], 7, v[226:227]
	v_lshl_add_u64 v[228:229], s[52:53], 0, v[228:229]
	v_lshl_add_u64 v[228:229], v[136:137], 4, v[228:229]
	global_load_dwordx4 v[214:217], v[228:229], off
	global_load_dwordx4 v[218:221], v[228:229], off offset:64
	v_add_u32_e32 v226, 176, v148
	v_lshlrev_b64 v[228:229], 7, v[226:227]
	v_lshl_add_u64 v[228:229], s[52:53], 0, v[228:229]
	v_lshl_add_u64 v[228:229], v[136:137], 4, v[228:229]
	global_load_dwordx4 v[222:225], v[228:229], off
	global_load_dwordx4 v[226:229], v[228:229], off offset:64
	s_waitcnt vmcnt(0)
	v_add_f32_e32 v166, v167, v166
	v_add_f32_e32 v168, v168, v169
	v_add_f32_e32 v166, v166, v168
	v_add_f32_e32 v170, v171, v170
	v_add_f32_e32 v172, v172, v173
	v_add_f32_e32 v170, v170, v172
	v_add_f32_e32 v166, v166, v170
	v_add_f32_e32 v174, v175, v174
	v_add_f32_e32 v176, v176, v177
	v_add_f32_e32 v174, v174, v176
	v_add_f32_e32 v178, v179, v178
	v_add_f32_e32 v180, v180, v181
	v_add_f32_e32 v178, v178, v180
	v_add_f32_e32 v174, v174, v178
	v_add_f32_e32 v182, v183, v182
	v_add_f32_e32 v184, v184, v185
	v_add_f32_e32 v182, v182, v184
	v_add_f32_e32 v186, v187, v186
	v_add_f32_e32 v188, v188, v189
	v_add_f32_e32 v186, v186, v188
	v_add_f32_e32 v182, v182, v186
	v_add_f32_e32 v190, v191, v190
	v_add_f32_e32 v192, v192, v193
	v_add_f32_e32 v190, v190, v192
	v_add_f32_e32 v194, v195, v194
	v_add_f32_e32 v196, v196, v197
	v_add_f32_e32 v194, v194, v196
	v_add_f32_e32 v190, v190, v194
	v_add_f32_e32 v198, v199, v198
	v_add_f32_e32 v200, v200, v201
	v_add_f32_e32 v198, v198, v200
	v_add_f32_e32 v202, v203, v202
	v_add_f32_e32 v204, v204, v205
	v_add_f32_e32 v202, v202, v204
	v_add_f32_e32 v198, v198, v202
	v_add_f32_e32 v206, v207, v206
	v_add_f32_e32 v208, v208, v209
	v_add_f32_e32 v206, v206, v208
	v_add_f32_e32 v210, v211, v210
	v_add_f32_e32 v212, v212, v213
	v_add_f32_e32 v210, v210, v212
	v_add_f32_e32 v206, v206, v210
	v_add_f32_e32 v214, v215, v214
	v_add_f32_e32 v216, v216, v217
	v_add_f32_e32 v214, v214, v216
	v_add_f32_e32 v218, v219, v218
	v_add_f32_e32 v220, v220, v221
	v_add_f32_e32 v218, v218, v220
	v_add_f32_e32 v214, v214, v218
	v_add_f32_e32 v222, v223, v222
	v_add_f32_e32 v224, v224, v225
	v_add_f32_e32 v222, v222, v224
	v_add_f32_e32 v226, v227, v226
	v_add_f32_e32 v228, v228, v229
	v_add_f32_e32 v226, v226, v228
	v_add_f32_e32 v222, v222, v226
	ds_bpermute_b32 v167, v153, v166
	ds_bpermute_b32 v175, v153, v174
	ds_bpermute_b32 v183, v153, v182
	ds_bpermute_b32 v191, v153, v190
	ds_bpermute_b32 v199, v153, v198
	ds_bpermute_b32 v207, v153, v206
	ds_bpermute_b32 v215, v153, v214
	ds_bpermute_b32 v223, v153, v222
	s_waitcnt lgkmcnt(0)
	v_add_f32_e32 v166, v166, v167
	v_add_f32_e32 v174, v174, v175
	v_add_f32_e32 v182, v182, v183
	v_add_f32_e32 v190, v190, v191
	v_add_f32_e32 v198, v198, v199
	v_add_f32_e32 v206, v206, v207
	v_add_f32_e32 v214, v214, v215
	v_add_f32_e32 v222, v222, v223
	ds_bpermute_b32 v167, v154, v166
	ds_bpermute_b32 v175, v154, v174
	ds_bpermute_b32 v183, v154, v182
	ds_bpermute_b32 v191, v154, v190
	ds_bpermute_b32 v199, v154, v198
	ds_bpermute_b32 v207, v154, v206
	ds_bpermute_b32 v215, v154, v214
	ds_bpermute_b32 v223, v154, v222
	s_waitcnt lgkmcnt(0)
	v_add_f32_e32 v166, v166, v167
	v_add_f32_e32 v174, v174, v175
	v_add_f32_e32 v182, v182, v183
	v_add_f32_e32 v190, v190, v191
	v_add_f32_e32 v198, v198, v199
	v_add_f32_e32 v206, v206, v207
	v_add_f32_e32 v214, v214, v215
	v_add_f32_e32 v222, v222, v223
	v_fmamk_f32 v166, v166, 0x3a000000, v158
	v_fmamk_f32 v174, v174, 0x3a000000, v158
	v_fmamk_f32 v182, v182, 0x3a000000, v158
	v_fmamk_f32 v190, v190, 0x3a000000, v158
	v_fmamk_f32 v198, v198, 0x3a000000, v158
	v_fmamk_f32 v206, v206, 0x3a000000, v158
	v_fmamk_f32 v214, v214, 0x3a000000, v158
	v_fmamk_f32 v222, v222, 0x3a000000, v158
	v_rsq_f32_e32 v166, v166
	v_rsq_f32_e32 v174, v174
	v_rsq_f32_e32 v182, v182
	v_rsq_f32_e32 v190, v190
	v_rsq_f32_e32 v198, v198
	v_rsq_f32_e32 v206, v206
	v_rsq_f32_e32 v214, v214
	v_rsq_f32_e32 v222, v222
	s_nop 0
	v_lshlrev_b64 v[146:147], 7, v[148:149]
	v_lshl_add_u64 v[146:147], s[52:53], 0, v[146:147]
	v_mov_b32_e32 v159, 0
	v_lshl_add_u64 v[146:147], v[136:137], 4, v[146:147]
	v_lshlrev_b64 v[160:161], 14, v[148:149]
	v_lshl_add_u64 v[160:161], s[50:51], 0, v[160:161]
	s_waitcnt lgkmcnt(0)
	v_lshl_add_u32 v146, s42, 8, v152
	s_waitcnt lgkmcnt(0)
	v_mov_b32_e32 v162, v166
	v_ashrrev_i32_e32 v147, 31, v146
	v_lshl_add_u64 v[160:161], v[146:147], 1, v[160:161]
	v_pk_mul_f32 v[120:121], v[120:121], v[162:163] op_sel_hi:[1,0]
	v_pk_mul_f32 v[124:125], v[124:125], v[162:163] op_sel_hi:[1,0]
	v_max_f32_e32 v120, 0, v120
	v_pk_mul_f32 v[126:127], v[126:127], v[162:163] op_sel_hi:[1,0]
	v_pk_mul_f32 v[122:123], v[122:123], v[162:163] op_sel_hi:[1,0]
	v_max_f32_e32 v125, 0, v125
	v_mul_f32_e32 v149, v120, v120
	v_max_f32_e32 v120, 0, v121
	v_mul_f32_e32 v121, v125, v125
	v_mul_f32_e32 v125, v120, v120
	v_max_f32_e32 v120, 0, v126
	v_max_f32_e32 v122, 0, v122
	v_max_f32_e32 v124, 0, v124
	v_mul_f32_e32 v126, v120, v120
	v_mul_f32_e32 v159, v122, v122
	v_max_f32_e32 v120, 0, v127
	v_max_f32_e32 v122, 0, v123
	v_mul_f32_e32 v124, v124, v124
	v_mul_f32_e32 v123, v120, v120
	v_mul_f32_e32 v127, v122, v122
	v_pk_mul_f32 v[114:115], v[114:115], v[162:163] op_sel_hi:[1,0]
	v_pk_mul_f32 v[112:113], v[112:113], v[162:163] op_sel_hi:[1,0]
	v_cvt_pk_bf16_f32 v120, v124, v121
	v_cvt_pk_bf16_f32 v121, v126, v123
	v_cvt_pk_bf16_f32 v122, v149, v125
	v_cvt_pk_bf16_f32 v123, v159, v127
	v_pk_mul_f32 v[118:119], v[118:119], v[162:163] op_sel_hi:[1,0]
	v_pk_mul_f32 v[116:117], v[116:117], v[162:163] op_sel_hi:[1,0]
	v_max_f32_e32 v112, 0, v112
	v_max_f32_e32 v113, 0, v113
	v_max_f32_e32 v114, 0, v114
	global_store_dwordx4 v[160:161], v[120:123], off
	v_max_f32_e32 v116, 0, v116
	v_max_f32_e32 v115, 0, v115
	v_mul_f32_e32 v120, v112, v112
	v_max_f32_e32 v112, 0, v117
	v_mul_f32_e32 v117, v113, v113
	v_max_f32_e32 v113, 0, v118
	v_mul_f32_e32 v118, v114, v114
	v_max_f32_e32 v114, 0, v119
	v_mul_f32_e32 v116, v116, v116
	v_mul_f32_e32 v112, v112, v112
	v_mul_f32_e32 v113, v113, v113
	v_mul_f32_e32 v114, v114, v114
	v_mul_f32_e32 v115, v115, v115
	v_cvt_pk_bf16_f32 v112, v116, v112
	v_cvt_pk_bf16_f32 v113, v113, v114
	v_cvt_pk_bf16_f32 v114, v120, v117
	v_cvt_pk_bf16_f32 v115, v118, v115
	global_store_dwordx4 v[160:161], v[112:115], off offset:256
	v_mov_b32_e32 v116, 0
	s_nop 0
	v_or_b32_e32 v112, 16, v148
	v_ashrrev_i32_e32 v113, 31, v112
	v_lshlrev_b64 v[114:115], 7, v[112:113]
	v_lshl_add_u64 v[114:115], s[52:53], 0, v[114:115]
	v_lshl_add_u64 v[114:115], v[136:137], 4, v[114:115]
	v_lshlrev_b64 v[112:113], 14, v[112:113]
	v_lshl_add_u64 v[112:113], s[50:51], 0, v[112:113]
	v_lshl_add_u64 v[112:113], v[146:147], 1, v[112:113]
	s_waitcnt lgkmcnt(0)
	s_waitcnt lgkmcnt(0)
	v_mov_b32_e32 v114, v174
	s_nop 0
	v_pk_mul_f32 v[108:109], v[108:109], v[114:115] op_sel_hi:[1,0]
	v_pk_mul_f32 v[106:107], v[106:107], v[114:115] op_sel_hi:[1,0]
	v_pk_mul_f32 v[104:105], v[104:105], v[114:115] op_sel_hi:[1,0]
	v_pk_mul_f32 v[110:111], v[110:111], v[114:115] op_sel_hi:[1,0]
	v_max_f32_e32 v104, 0, v104
	v_max_f32_e32 v109, 0, v109
	v_max_f32_e32 v105, 0, v105
	v_max_f32_e32 v106, 0, v106
	v_max_f32_e32 v108, 0, v108
	v_mul_f32_e32 v115, v104, v104
	v_mul_f32_e32 v104, v109, v109
	v_mul_f32_e32 v109, v105, v105
	v_max_f32_e32 v105, 0, v110
	v_mul_f32_e32 v110, v106, v106
	v_max_f32_e32 v106, 0, v111
	v_max_f32_e32 v107, 0, v107
	v_mul_f32_e32 v108, v108, v108
	v_mul_f32_e32 v105, v105, v105
	v_mul_f32_e32 v106, v106, v106
	v_mul_f32_e32 v107, v107, v107
	v_pk_mul_f32 v[98:99], v[98:99], v[114:115] op_sel_hi:[1,0]
	v_pk_mul_f32 v[96:97], v[96:97], v[114:115] op_sel_hi:[1,0]
	v_cvt_pk_bf16_f32 v104, v108, v104
	v_cvt_pk_bf16_f32 v105, v105, v106
	v_cvt_pk_bf16_f32 v106, v115, v109
	v_cvt_pk_bf16_f32 v107, v110, v107
	v_pk_mul_f32 v[102:103], v[102:103], v[114:115] op_sel_hi:[1,0]
	v_pk_mul_f32 v[100:101], v[100:101], v[114:115] op_sel_hi:[1,0]
	v_max_f32_e32 v96, 0, v96
	v_max_f32_e32 v97, 0, v97
	v_max_f32_e32 v98, 0, v98
	global_store_dwordx4 v[112:113], v[104:107], off
	v_max_f32_e32 v100, 0, v100
	v_max_f32_e32 v99, 0, v99
	v_mul_f32_e32 v104, v96, v96
	v_max_f32_e32 v96, 0, v101
	v_mul_f32_e32 v101, v97, v97
	v_max_f32_e32 v97, 0, v102
	v_mul_f32_e32 v102, v98, v98
	v_max_f32_e32 v98, 0, v103
	v_mul_f32_e32 v100, v100, v100
	v_mul_f32_e32 v96, v96, v96
	v_mul_f32_e32 v97, v97, v97
	v_mul_f32_e32 v98, v98, v98
	v_mul_f32_e32 v99, v99, v99
	v_cvt_pk_bf16_f32 v96, v100, v96
	v_cvt_pk_bf16_f32 v97, v97, v98
	v_cvt_pk_bf16_f32 v98, v104, v101
	v_cvt_pk_bf16_f32 v99, v102, v99
	global_store_dwordx4 v[112:113], v[96:99], off offset:256
	v_mov_b32_e32 v100, 0
	s_nop 0
	v_or_b32_e32 v96, 32, v148
	v_ashrrev_i32_e32 v97, 31, v96
	v_lshlrev_b64 v[98:99], 7, v[96:97]
	v_lshl_add_u64 v[98:99], s[52:53], 0, v[98:99]
	v_lshl_add_u64 v[98:99], v[136:137], 4, v[98:99]
	v_lshlrev_b64 v[96:97], 14, v[96:97]
	v_lshl_add_u64 v[96:97], s[50:51], 0, v[96:97]
	v_lshl_add_u64 v[96:97], v[146:147], 1, v[96:97]
	s_waitcnt lgkmcnt(0)
	s_waitcnt lgkmcnt(0)
	v_mov_b32_e32 v98, v182
	s_nop 0
	v_pk_mul_f32 v[92:93], v[92:93], v[98:99] op_sel_hi:[1,0]
	v_pk_mul_f32 v[90:91], v[90:91], v[98:99] op_sel_hi:[1,0]
	v_pk_mul_f32 v[88:89], v[88:89], v[98:99] op_sel_hi:[1,0]
	v_pk_mul_f32 v[94:95], v[94:95], v[98:99] op_sel_hi:[1,0]
	v_max_f32_e32 v88, 0, v88
	v_max_f32_e32 v93, 0, v93
	v_max_f32_e32 v89, 0, v89
	v_max_f32_e32 v90, 0, v90
	v_max_f32_e32 v92, 0, v92
	v_mul_f32_e32 v99, v88, v88
	v_mul_f32_e32 v88, v93, v93
	v_mul_f32_e32 v93, v89, v89
	v_max_f32_e32 v89, 0, v94
	v_mul_f32_e32 v94, v90, v90
	v_max_f32_e32 v90, 0, v95
	v_max_f32_e32 v91, 0, v91
	v_mul_f32_e32 v92, v92, v92
	v_mul_f32_e32 v89, v89, v89
	v_mul_f32_e32 v90, v90, v90
	v_mul_f32_e32 v91, v91, v91
	v_pk_mul_f32 v[82:83], v[82:83], v[98:99] op_sel_hi:[1,0]
	v_pk_mul_f32 v[80:81], v[80:81], v[98:99] op_sel_hi:[1,0]
	v_cvt_pk_bf16_f32 v88, v92, v88
	v_cvt_pk_bf16_f32 v89, v89, v90
	v_cvt_pk_bf16_f32 v90, v99, v93
	v_cvt_pk_bf16_f32 v91, v94, v91
	v_pk_mul_f32 v[86:87], v[86:87], v[98:99] op_sel_hi:[1,0]
	v_pk_mul_f32 v[84:85], v[84:85], v[98:99] op_sel_hi:[1,0]
	v_max_f32_e32 v80, 0, v80
	v_max_f32_e32 v81, 0, v81
	v_max_f32_e32 v82, 0, v82
	global_store_dwordx4 v[96:97], v[88:91], off
	v_max_f32_e32 v84, 0, v84
	v_max_f32_e32 v83, 0, v83
	v_mul_f32_e32 v88, v80, v80
	v_max_f32_e32 v80, 0, v85
	v_mul_f32_e32 v85, v81, v81
	v_max_f32_e32 v81, 0, v86
	v_mul_f32_e32 v86, v82, v82
	v_max_f32_e32 v82, 0, v87
	v_mul_f32_e32 v84, v84, v84
	v_mul_f32_e32 v80, v80, v80
	v_mul_f32_e32 v81, v81, v81
	v_mul_f32_e32 v82, v82, v82
	v_mul_f32_e32 v83, v83, v83
	v_cvt_pk_bf16_f32 v80, v84, v80
	v_cvt_pk_bf16_f32 v81, v81, v82
	v_cvt_pk_bf16_f32 v82, v88, v85
	v_cvt_pk_bf16_f32 v83, v86, v83
	global_store_dwordx4 v[96:97], v[80:83], off offset:256
	v_mov_b32_e32 v84, 0
	s_nop 0
	v_or_b32_e32 v80, 48, v148
	v_ashrrev_i32_e32 v81, 31, v80
	v_lshlrev_b64 v[82:83], 7, v[80:81]
	v_lshl_add_u64 v[82:83], s[52:53], 0, v[82:83]
	v_lshl_add_u64 v[82:83], v[136:137], 4, v[82:83]
	v_lshlrev_b64 v[80:81], 14, v[80:81]
	v_lshl_add_u64 v[80:81], s[50:51], 0, v[80:81]
	v_lshl_add_u64 v[80:81], v[146:147], 1, v[80:81]
	s_waitcnt lgkmcnt(0)
	s_waitcnt lgkmcnt(0)
	v_mov_b32_e32 v82, v190
	s_nop 0
	v_pk_mul_f32 v[76:77], v[76:77], v[82:83] op_sel_hi:[1,0]
	v_pk_mul_f32 v[74:75], v[74:75], v[82:83] op_sel_hi:[1,0]
	v_pk_mul_f32 v[72:73], v[72:73], v[82:83] op_sel_hi:[1,0]
	v_pk_mul_f32 v[78:79], v[78:79], v[82:83] op_sel_hi:[1,0]
	v_max_f32_e32 v72, 0, v72
	v_max_f32_e32 v77, 0, v77
	v_max_f32_e32 v73, 0, v73
	v_max_f32_e32 v74, 0, v74
	v_max_f32_e32 v76, 0, v76
	v_mul_f32_e32 v83, v72, v72
	v_mul_f32_e32 v72, v77, v77
	v_mul_f32_e32 v77, v73, v73
	v_max_f32_e32 v73, 0, v78
	v_mul_f32_e32 v78, v74, v74
	v_max_f32_e32 v74, 0, v79
	v_max_f32_e32 v75, 0, v75
	v_mul_f32_e32 v76, v76, v76
	v_mul_f32_e32 v73, v73, v73
	v_mul_f32_e32 v74, v74, v74
	v_mul_f32_e32 v75, v75, v75
	v_pk_mul_f32 v[66:67], v[66:67], v[82:83] op_sel_hi:[1,0]
	v_pk_mul_f32 v[64:65], v[64:65], v[82:83] op_sel_hi:[1,0]
	v_cvt_pk_bf16_f32 v72, v76, v72
	v_cvt_pk_bf16_f32 v73, v73, v74
	v_cvt_pk_bf16_f32 v74, v83, v77
	v_cvt_pk_bf16_f32 v75, v78, v75
	v_pk_mul_f32 v[70:71], v[70:71], v[82:83] op_sel_hi:[1,0]
	v_pk_mul_f32 v[68:69], v[68:69], v[82:83] op_sel_hi:[1,0]
	v_max_f32_e32 v64, 0, v64
	v_max_f32_e32 v65, 0, v65
	v_max_f32_e32 v66, 0, v66
	global_store_dwordx4 v[80:81], v[72:75], off
	v_max_f32_e32 v68, 0, v68
	v_max_f32_e32 v67, 0, v67
	v_mul_f32_e32 v72, v64, v64
	v_max_f32_e32 v64, 0, v69
	v_mul_f32_e32 v69, v65, v65
	v_max_f32_e32 v65, 0, v70
	v_mul_f32_e32 v70, v66, v66
	v_max_f32_e32 v66, 0, v71
	v_mul_f32_e32 v68, v68, v68
	v_mul_f32_e32 v64, v64, v64
	v_mul_f32_e32 v65, v65, v65
	v_mul_f32_e32 v66, v66, v66
	v_mul_f32_e32 v67, v67, v67
	v_cvt_pk_bf16_f32 v64, v68, v64
	v_cvt_pk_bf16_f32 v65, v65, v66
	v_cvt_pk_bf16_f32 v66, v72, v69
	v_cvt_pk_bf16_f32 v67, v70, v67
	global_store_dwordx4 v[80:81], v[64:67], off offset:256
	v_mov_b32_e32 v68, 0
	s_nop 0
	v_add_u32_e32 v64, 0x80, v148
	v_ashrrev_i32_e32 v65, 31, v64
	v_lshlrev_b64 v[66:67], 7, v[64:65]
	v_lshl_add_u64 v[66:67], s[52:53], 0, v[66:67]
	v_lshl_add_u64 v[66:67], v[136:137], 4, v[66:67]
	v_lshlrev_b64 v[64:65], 14, v[64:65]
	v_lshl_add_u64 v[64:65], s[50:51], 0, v[64:65]
	v_lshl_add_u64 v[64:65], v[146:147], 1, v[64:65]
	s_waitcnt lgkmcnt(0)
	s_waitcnt lgkmcnt(0)
	v_mov_b32_e32 v66, v198
	s_nop 0
	v_pk_mul_f32 v[60:61], v[60:61], v[66:67] op_sel_hi:[1,0]
	v_pk_mul_f32 v[58:59], v[58:59], v[66:67] op_sel_hi:[1,0]
	v_pk_mul_f32 v[56:57], v[56:57], v[66:67] op_sel_hi:[1,0]
	v_pk_mul_f32 v[62:63], v[62:63], v[66:67] op_sel_hi:[1,0]
	v_max_f32_e32 v56, 0, v56
	v_max_f32_e32 v61, 0, v61
	v_max_f32_e32 v57, 0, v57
	v_max_f32_e32 v58, 0, v58
	v_max_f32_e32 v60, 0, v60
	v_mul_f32_e32 v67, v56, v56
	v_mul_f32_e32 v56, v61, v61
	v_mul_f32_e32 v61, v57, v57
	v_max_f32_e32 v57, 0, v62
	v_mul_f32_e32 v62, v58, v58
	v_max_f32_e32 v58, 0, v63
	v_max_f32_e32 v59, 0, v59
	v_mul_f32_e32 v60, v60, v60
	v_mul_f32_e32 v57, v57, v57
	v_mul_f32_e32 v58, v58, v58
	v_mul_f32_e32 v59, v59, v59
	v_pk_mul_f32 v[50:51], v[50:51], v[66:67] op_sel_hi:[1,0]
	v_pk_mul_f32 v[48:49], v[48:49], v[66:67] op_sel_hi:[1,0]
	v_cvt_pk_bf16_f32 v56, v60, v56
	v_cvt_pk_bf16_f32 v57, v57, v58
	v_cvt_pk_bf16_f32 v58, v67, v61
	v_cvt_pk_bf16_f32 v59, v62, v59
	v_pk_mul_f32 v[54:55], v[54:55], v[66:67] op_sel_hi:[1,0]
	v_pk_mul_f32 v[52:53], v[52:53], v[66:67] op_sel_hi:[1,0]
	v_max_f32_e32 v48, 0, v48
	v_max_f32_e32 v49, 0, v49
	v_max_f32_e32 v50, 0, v50
	global_store_dwordx4 v[64:65], v[56:59], off
	v_max_f32_e32 v52, 0, v52
	v_max_f32_e32 v51, 0, v51
	v_mul_f32_e32 v56, v48, v48
	v_max_f32_e32 v48, 0, v53
	v_mul_f32_e32 v53, v49, v49
	v_max_f32_e32 v49, 0, v54
	v_mul_f32_e32 v54, v50, v50
	v_max_f32_e32 v50, 0, v55
	v_mul_f32_e32 v52, v52, v52
	v_mul_f32_e32 v48, v48, v48
	v_mul_f32_e32 v49, v49, v49
	v_mul_f32_e32 v50, v50, v50
	v_mul_f32_e32 v51, v51, v51
	v_cvt_pk_bf16_f32 v48, v52, v48
	v_cvt_pk_bf16_f32 v49, v49, v50
	v_cvt_pk_bf16_f32 v50, v56, v53
	v_cvt_pk_bf16_f32 v51, v54, v51
	global_store_dwordx4 v[64:65], v[48:51], off offset:256
	v_mov_b32_e32 v52, 0
	s_nop 0
	v_add_u32_e32 v48, 0x90, v148
	v_ashrrev_i32_e32 v49, 31, v48
	v_lshlrev_b64 v[50:51], 7, v[48:49]
	v_lshl_add_u64 v[50:51], s[52:53], 0, v[50:51]
	v_lshl_add_u64 v[50:51], v[136:137], 4, v[50:51]
	v_lshlrev_b64 v[48:49], 14, v[48:49]
	v_lshl_add_u64 v[48:49], s[50:51], 0, v[48:49]
	v_lshl_add_u64 v[48:49], v[146:147], 1, v[48:49]
	s_waitcnt lgkmcnt(0)
	s_waitcnt lgkmcnt(0)
	v_mov_b32_e32 v50, v206
	s_nop 0
	v_pk_mul_f32 v[44:45], v[44:45], v[50:51] op_sel_hi:[1,0]
	v_pk_mul_f32 v[42:43], v[42:43], v[50:51] op_sel_hi:[1,0]
	v_pk_mul_f32 v[40:41], v[40:41], v[50:51] op_sel_hi:[1,0]
	v_pk_mul_f32 v[46:47], v[46:47], v[50:51] op_sel_hi:[1,0]
	v_max_f32_e32 v40, 0, v40
	v_max_f32_e32 v45, 0, v45
	v_max_f32_e32 v41, 0, v41
	v_max_f32_e32 v42, 0, v42
	v_max_f32_e32 v44, 0, v44
	v_mul_f32_e32 v51, v40, v40
	v_mul_f32_e32 v40, v45, v45
	v_mul_f32_e32 v45, v41, v41
	v_max_f32_e32 v41, 0, v46
	v_mul_f32_e32 v46, v42, v42
	v_max_f32_e32 v42, 0, v47
	v_max_f32_e32 v43, 0, v43
	v_mul_f32_e32 v44, v44, v44
	v_mul_f32_e32 v41, v41, v41
	v_mul_f32_e32 v42, v42, v42
	v_mul_f32_e32 v43, v43, v43
	v_pk_mul_f32 v[34:35], v[34:35], v[50:51] op_sel_hi:[1,0]
	v_pk_mul_f32 v[32:33], v[32:33], v[50:51] op_sel_hi:[1,0]
	v_cvt_pk_bf16_f32 v40, v44, v40
	v_cvt_pk_bf16_f32 v41, v41, v42
	v_cvt_pk_bf16_f32 v42, v51, v45
	v_cvt_pk_bf16_f32 v43, v46, v43
	v_pk_mul_f32 v[38:39], v[38:39], v[50:51] op_sel_hi:[1,0]
	v_pk_mul_f32 v[36:37], v[36:37], v[50:51] op_sel_hi:[1,0]
	v_max_f32_e32 v32, 0, v32
	v_max_f32_e32 v33, 0, v33
	v_max_f32_e32 v34, 0, v34
	global_store_dwordx4 v[48:49], v[40:43], off
	v_max_f32_e32 v36, 0, v36
	v_max_f32_e32 v35, 0, v35
	v_mul_f32_e32 v40, v32, v32
	v_max_f32_e32 v32, 0, v37
	v_mul_f32_e32 v37, v33, v33
	v_max_f32_e32 v33, 0, v38
	v_mul_f32_e32 v38, v34, v34
	v_max_f32_e32 v34, 0, v39
	v_mul_f32_e32 v36, v36, v36
	v_mul_f32_e32 v32, v32, v32
	v_mul_f32_e32 v33, v33, v33
	v_mul_f32_e32 v34, v34, v34
	v_mul_f32_e32 v35, v35, v35
	v_cvt_pk_bf16_f32 v32, v36, v32
	v_cvt_pk_bf16_f32 v33, v33, v34
	v_cvt_pk_bf16_f32 v34, v40, v37
	v_cvt_pk_bf16_f32 v35, v38, v35
	global_store_dwordx4 v[48:49], v[32:35], off offset:256
	v_mov_b32_e32 v36, 0
	s_nop 0
	v_add_u32_e32 v32, 0xa0, v148
	v_ashrrev_i32_e32 v33, 31, v32
	v_lshlrev_b64 v[34:35], 7, v[32:33]
	v_lshl_add_u64 v[34:35], s[52:53], 0, v[34:35]
	v_lshl_add_u64 v[34:35], v[136:137], 4, v[34:35]
	v_lshlrev_b64 v[32:33], 14, v[32:33]
	v_lshl_add_u64 v[32:33], s[50:51], 0, v[32:33]
	v_lshl_add_u64 v[32:33], v[146:147], 1, v[32:33]
	s_waitcnt lgkmcnt(0)
	s_waitcnt lgkmcnt(0)
	v_mov_b32_e32 v34, v214
	s_nop 0
	v_pk_mul_f32 v[28:29], v[28:29], v[34:35] op_sel_hi:[1,0]
	v_pk_mul_f32 v[26:27], v[26:27], v[34:35] op_sel_hi:[1,0]
	v_pk_mul_f32 v[24:25], v[24:25], v[34:35] op_sel_hi:[1,0]
	v_pk_mul_f32 v[30:31], v[30:31], v[34:35] op_sel_hi:[1,0]
	v_max_f32_e32 v24, 0, v24
	v_max_f32_e32 v29, 0, v29
	v_max_f32_e32 v25, 0, v25
	v_max_f32_e32 v26, 0, v26
	v_max_f32_e32 v28, 0, v28
	v_mul_f32_e32 v35, v24, v24
	v_mul_f32_e32 v24, v29, v29
	v_mul_f32_e32 v29, v25, v25
	v_max_f32_e32 v25, 0, v30
	v_mul_f32_e32 v30, v26, v26
	v_max_f32_e32 v26, 0, v31
	v_max_f32_e32 v27, 0, v27
	v_mul_f32_e32 v28, v28, v28
	v_mul_f32_e32 v25, v25, v25
	v_mul_f32_e32 v26, v26, v26
	v_mul_f32_e32 v27, v27, v27
	v_pk_mul_f32 v[18:19], v[18:19], v[34:35] op_sel_hi:[1,0]
	v_pk_mul_f32 v[16:17], v[16:17], v[34:35] op_sel_hi:[1,0]
	v_cvt_pk_bf16_f32 v24, v28, v24
	v_cvt_pk_bf16_f32 v25, v25, v26
	v_cvt_pk_bf16_f32 v26, v35, v29
	v_cvt_pk_bf16_f32 v27, v30, v27
	v_pk_mul_f32 v[22:23], v[22:23], v[34:35] op_sel_hi:[1,0]
	v_pk_mul_f32 v[20:21], v[20:21], v[34:35] op_sel_hi:[1,0]
	v_max_f32_e32 v16, 0, v16
	v_max_f32_e32 v17, 0, v17
	v_max_f32_e32 v18, 0, v18
	global_store_dwordx4 v[32:33], v[24:27], off
	v_max_f32_e32 v20, 0, v20
	v_max_f32_e32 v19, 0, v19
	v_mul_f32_e32 v24, v16, v16
	v_max_f32_e32 v16, 0, v21
	v_mul_f32_e32 v21, v17, v17
	v_max_f32_e32 v17, 0, v22
	v_mul_f32_e32 v22, v18, v18
	v_max_f32_e32 v18, 0, v23
	v_mul_f32_e32 v20, v20, v20
	v_mul_f32_e32 v16, v16, v16
	v_mul_f32_e32 v17, v17, v17
	v_mul_f32_e32 v18, v18, v18
	v_mul_f32_e32 v19, v19, v19
	v_cvt_pk_bf16_f32 v16, v20, v16
	v_cvt_pk_bf16_f32 v17, v17, v18
	v_cvt_pk_bf16_f32 v18, v24, v21
	v_cvt_pk_bf16_f32 v19, v22, v19
	global_store_dwordx4 v[32:33], v[16:19], off offset:256
	v_mov_b32_e32 v20, 0
	s_nop 0
	v_add_u32_e32 v16, 0xb0, v148
	v_ashrrev_i32_e32 v17, 31, v16
	v_lshlrev_b64 v[18:19], 7, v[16:17]
	v_lshl_add_u64 v[18:19], s[52:53], 0, v[18:19]
	v_lshl_add_u64 v[18:19], v[136:137], 4, v[18:19]
	v_lshlrev_b64 v[16:17], 14, v[16:17]
	v_lshl_add_u64 v[16:17], s[50:51], 0, v[16:17]
	v_lshl_add_u64 v[16:17], v[146:147], 1, v[16:17]
	s_andn2_b64 vcc, exec, s[14:15]
	s_waitcnt lgkmcnt(0)
	s_mov_b64 s[14:15], -1
	s_waitcnt lgkmcnt(0)
	v_mov_b32_e32 v18, v222
	s_nop 0
	v_pk_mul_f32 v[12:13], v[12:13], v[18:19] op_sel_hi:[1,0]
	v_pk_mul_f32 v[10:11], v[10:11], v[18:19] op_sel_hi:[1,0]
	v_pk_mul_f32 v[8:9], v[8:9], v[18:19] op_sel_hi:[1,0]
	v_pk_mul_f32 v[14:15], v[14:15], v[18:19] op_sel_hi:[1,0]
	v_max_f32_e32 v8, 0, v8
	v_max_f32_e32 v13, 0, v13
	v_max_f32_e32 v9, 0, v9
	v_max_f32_e32 v10, 0, v10
	v_max_f32_e32 v12, 0, v12
	v_mul_f32_e32 v19, v8, v8
	v_mul_f32_e32 v8, v13, v13
	v_mul_f32_e32 v13, v9, v9
	v_max_f32_e32 v9, 0, v14
	v_mul_f32_e32 v14, v10, v10
	v_max_f32_e32 v10, 0, v15
	v_max_f32_e32 v11, 0, v11
	v_mul_f32_e32 v12, v12, v12
	v_mul_f32_e32 v9, v9, v9
	v_mul_f32_e32 v10, v10, v10
	v_mul_f32_e32 v11, v11, v11
	v_pk_mul_f32 v[2:3], v[2:3], v[18:19] op_sel_hi:[1,0]
	v_pk_mul_f32 v[0:1], v[0:1], v[18:19] op_sel_hi:[1,0]
	v_cvt_pk_bf16_f32 v8, v12, v8
	v_cvt_pk_bf16_f32 v9, v9, v10
	v_cvt_pk_bf16_f32 v10, v19, v13
	v_cvt_pk_bf16_f32 v11, v14, v11
	v_pk_mul_f32 v[6:7], v[6:7], v[18:19] op_sel_hi:[1,0]
	v_pk_mul_f32 v[4:5], v[4:5], v[18:19] op_sel_hi:[1,0]
	v_max_f32_e32 v0, 0, v0
	v_max_f32_e32 v1, 0, v1
	v_max_f32_e32 v2, 0, v2
	global_store_dwordx4 v[16:17], v[8:11], off
	v_max_f32_e32 v4, 0, v4
	v_max_f32_e32 v3, 0, v3
	v_mul_f32_e32 v8, v0, v0
	v_max_f32_e32 v0, 0, v5
	v_mul_f32_e32 v5, v1, v1
	v_max_f32_e32 v1, 0, v6
	v_mul_f32_e32 v6, v2, v2
	v_max_f32_e32 v2, 0, v7
	v_mul_f32_e32 v4, v4, v4
	v_mul_f32_e32 v0, v0, v0
	v_mul_f32_e32 v1, v1, v1
	v_mul_f32_e32 v2, v2, v2
	v_mul_f32_e32 v3, v3, v3
	v_cvt_pk_bf16_f32 v0, v4, v0
	v_cvt_pk_bf16_f32 v1, v1, v2
	v_cvt_pk_bf16_f32 v2, v8, v5
	v_cvt_pk_bf16_f32 v3, v6, v3
	global_store_dwordx4 v[16:17], v[0:3], off offset:256
	s_cbranch_vccnz .LBB0_2797
	s_and_b64 vcc, exec, s[10:11]
	s_cbranch_vccnz .LBB0_2796
	s_barrier
	s_branch .LBB0_2796
